# GEMM K-loops: MFMA-block end barrier issued three MFMAs early, those three run at priority 2 so the released half does not starve them
# baseline (speedup 1.0000x reference)
; #define PG8_STAGE(bufoff, gbase, voff) do { _Pragma("unroll") for (int _i = 0; _i < 2; ++_i) \
;         __builtin_amdgcn_global_load_lds((const unsigned*)((const char*)(gbase) + (voff)[_i]), (PG8_LAS unsigned*)(lds + (bufoff) + ldsw + _i * 8192), 16, 0, 0); } while (0)
; #define PG8_LDA(dst, b, h) do { _Pragma("unroll") for (int m = 0; m < 4; ++m) _Pragma("unroll") for (int k = 0; k < 2; ++k) dst[m][k] = *(const PG8_LAS bf16x8*)(lds + PG8_SA(b, h) + aoff + m * 2048 + k * 1024); } while (0)
; #define PG8_LDB(dst, b, h) do { _Pragma("unroll") for (int n = 0; n < 2; ++n) _Pragma("unroll") for (int k = 0; k < 2; ++k) dst[n][k] = *(const PG8_LAS bf16x8*)(lds + PG8_SB(b, h) + boff + n * 2048 + k * 1024); } while (0)
; #define PG8_MMA(ai, bj, At, Bt) do { __builtin_amdgcn_s_setprio(1); _Pragma("unroll") for (int m = 0; m < 4; ++m) _Pragma("unroll") for (int n = 0; n < 2; ++n) _Pragma("unroll") for (int k = 0; k < 2; ++k) \
;         acc[ai][bj][m][n] = __builtin_amdgcn_mfma_f32_16x16x32_bf16(Bt[n][k], At[m][k], acc[ai][bj][m][n], 0, 0, 0); __builtin_amdgcn_s_setprio(0); } while (0)
; #define PG8_WAIT_V(n) asm volatile("s_waitcnt vmcnt(" #n ")" ::: "memory")
; #define PG8_WAIT_L(n) asm volatile("s_waitcnt lgkmcnt(" #n ")" ::: "memory")
; #define PG8_BAR __builtin_amdgcn_s_barrier()
; #define PG8_SCHED __builtin_amdgcn_sched_barrier(0)
; template <class Epi, class Sched, bool ALIGN_EPI = false, bool SP2 = false>
; __device__ __forceinline__ void gemm_phase(PG8_LAS unsigned char* lds, const Gemm g, const Sched& S, const Epi& E) {
;     ...
;             PG8_LDB(B0, 0, 0); PG8_LDB(B1, 0, 1); PG8_SCHED; PG8_LDA(At, 0, 0); PG8_STAGE(PG8_SA(1, 1), a1 + hstep, voffA);
;             PG8_WAIT_V(8); PG8_WAIT_L(0); PG8_BAR; PG8_MMA(0, 0, At, B0); PG8_MMA(0, 1, At, B1); PG8_BAR; PG8_SCHED;
;             PG8_LDA(At, 0, 1); PG8_STAGE(PG8_SB(0, 0), b2, voffB); PG8_STAGE(PG8_SB(0, 1), b2 + hstep, voffB); PG8_STAGE(PG8_SA(0, 0), a2, voffA);
.LBB0_121:
	s_add_u32 s46, s44, 0xfffc0080
	s_addc_u32 s47, s45, -1
	s_add_i32 s64, 0, 0x10000
	s_cmp_eq_u32 s63, 12
	s_cselect_b32 s49, s41, s47
	s_cselect_b32 s48, s40, s46
	v_add_u32_e32 v146, s64, v149
	s_cselect_b32 s47, s37, s62
	s_cselect_b32 s46, s39, s61
	s_add_i32 s67, 0, 0x14000
	ds_read_b128 v[152:155], v146
	ds_read_b128 v[156:159], v146 offset:1024
	ds_read_b128 v[160:163], v146 offset:2048
	ds_read_b128 v[174:177], v146 offset:3072
	v_add_u32_e32 v146, s67, v149
	ds_read_b128 v[178:181], v146
	ds_read_b128 v[182:185], v146 offset:1024
	ds_read_b128 v[186:189], v146 offset:2048
	ds_read_b128 v[190:193], v146 offset:3072
	v_lshl_add_u64 v[146:147], s[44:45], 0, v[142:143]
	s_add_i32 m0, s52, 0xc000
	ds_read_b128 v[194:197], v151
	ds_read_b128 v[198:201], v151 offset:1024
	ds_read_b128 v[202:205], v151 offset:2048
	ds_read_b128 v[206:209], v151 offset:3072
	ds_read_b128 v[210:213], v151 offset:4096
	ds_read_b128 v[214:217], v151 offset:5120
	ds_read_b128 v[218:221], v151 offset:6144
	ds_read_b128 v[222:225], v151 offset:7168
	global_load_lds_dwordx4 v[146:147], off
	v_lshl_add_u64 v[146:147], s[44:45], 0, v[144:145]
	s_add_i32 m0, s52, 0xe000
	s_nop 0
	global_load_lds_dwordx4 v[146:147], off
	s_waitcnt vmcnt(8)
	s_waitcnt lgkmcnt(0)
	s_barrier
	s_setprio 1
	s_waitcnt lgkmcnt(0)
	v_mfma_f32_16x16x32_bf16 v[126:129], v[152:155], v[194:197], v[126:129]
	v_mfma_f32_16x16x32_bf16 v[122:125], v[160:163], v[194:197], v[122:125]
	v_mfma_f32_16x16x32_bf16 v[118:121], v[152:155], v[202:205], v[118:121]
	v_mfma_f32_16x16x32_bf16 v[110:113], v[160:163], v[202:205], v[110:113]
	v_mfma_f32_16x16x32_bf16 v[102:105], v[152:155], v[210:213], v[102:105]
	v_mfma_f32_16x16x32_bf16 v[94:97], v[160:163], v[210:213], v[94:97]
	v_mfma_f32_16x16x32_bf16 v[86:89], v[152:155], v[218:221], v[86:89]
	v_mfma_f32_16x16x32_bf16 v[78:81], v[160:163], v[218:221], v[78:81]
	v_mfma_f32_16x16x32_bf16 v[126:129], v[156:159], v[198:201], v[126:129]
	v_mfma_f32_16x16x32_bf16 v[122:125], v[174:177], v[198:201], v[122:125]
	v_mfma_f32_16x16x32_bf16 v[118:121], v[156:159], v[206:209], v[118:121]
	v_mfma_f32_16x16x32_bf16 v[110:113], v[174:177], v[206:209], v[110:113]
	v_mfma_f32_16x16x32_bf16 v[102:105], v[156:159], v[214:217], v[102:105]
	v_mfma_f32_16x16x32_bf16 v[94:97], v[174:177], v[214:217], v[94:97]
	v_mfma_f32_16x16x32_bf16 v[86:89], v[156:159], v[222:225], v[86:89]
	v_mfma_f32_16x16x32_bf16 v[78:81], v[174:177], v[222:225], v[78:81]
	s_setprio 0
	s_setprio 1
	v_mfma_f32_16x16x32_bf16 v[114:117], v[178:181], v[194:197], v[114:117]
	v_mfma_f32_16x16x32_bf16 v[106:109], v[186:189], v[194:197], v[106:109]
	v_mfma_f32_16x16x32_bf16 v[98:101], v[178:181], v[202:205], v[98:101]
	v_mfma_f32_16x16x32_bf16 v[90:93], v[186:189], v[202:205], v[90:93]
	v_mfma_f32_16x16x32_bf16 v[82:85], v[178:181], v[210:213], v[82:85]
	v_mfma_f32_16x16x32_bf16 v[74:77], v[186:189], v[210:213], v[74:77]
	v_mfma_f32_16x16x32_bf16 v[70:73], v[178:181], v[218:221], v[70:73]
	v_mfma_f32_16x16x32_bf16 v[66:69], v[186:189], v[218:221], v[66:69]
	v_mfma_f32_16x16x32_bf16 v[114:117], v[182:185], v[198:201], v[114:117]
	v_mfma_f32_16x16x32_bf16 v[106:109], v[190:193], v[198:201], v[106:109]
	v_mfma_f32_16x16x32_bf16 v[98:101], v[182:185], v[206:209], v[98:101]
	v_mfma_f32_16x16x32_bf16 v[90:93], v[190:193], v[206:209], v[90:93]
	v_mfma_f32_16x16x32_bf16 v[82:85], v[182:185], v[214:217], v[82:85]
	s_setprio 2
	s_barrier
	v_mfma_f32_16x16x32_bf16 v[74:77], v[190:193], v[214:217], v[74:77]
	v_mfma_f32_16x16x32_bf16 v[70:73], v[182:185], v[222:225], v[70:73]
	v_mfma_f32_16x16x32_bf16 v[66:69], v[190:193], v[222:225], v[66:69]
	s_setprio 0
	s_add_i32 s64, s64, s34
	v_lshl_add_u64 v[146:147], s[46:47], 0, v[130:131]
	s_mov_b32 m0, s64
	ds_read_b128 v[194:197], v151 offset:16384
	ds_read_b128 v[198:201], v151 offset:17408
	ds_read_b128 v[202:205], v151 offset:18432
	ds_read_b128 v[206:209], v151 offset:19456
	ds_read_b128 v[210:213], v151 offset:20480
	ds_read_b128 v[214:217], v151 offset:21504
	ds_read_b128 v[218:221], v151 offset:22528
	ds_read_b128 v[222:225], v151 offset:23552
	global_load_lds_dwordx4 v[146:147], off
	s_add_i32 m0, s64, 0x2000
	s_add_u32 s64, s46, 0x40000
	v_lshl_add_u64 v[226:227], s[46:47], 0, v[136:137]
	s_addc_u32 s65, s47, 0
	s_add_i32 s67, s67, s34
	global_load_lds_dwordx4 v[226:227], off
	v_lshl_add_u64 v[228:229], s[64:65], 0, v[130:131]
	s_mov_b32 m0, s67
	v_lshl_add_u64 v[230:231], s[48:49], 0, v[138:139]
	global_load_lds_dwordx4 v[228:229], off
	v_lshl_add_u64 v[228:229], s[64:65], 0, v[136:137]
	s_add_i32 m0, s67, 0x2000
	s_nop 0
	global_load_lds_dwordx4 v[228:229], off
	v_lshl_add_u64 v[228:229], s[48:49], 0, v[140:141]
	s_mov_b32 m0, s52
	s_nop 0
	global_load_lds_dwordx4 v[228:229], off
	s_mov_b32 m0, s53
	s_nop 0
	global_load_lds_dwordx4 v[230:231], off
	s_waitcnt vmcnt(8)
	s_waitcnt lgkmcnt(0)
	s_barrier
; #define PG8_STAGE(bufoff, gbase, voff) do { _Pragma("unroll") for (int _i = 0; _i < 2; ++_i) \
;         __builtin_amdgcn_global_load_lds((const unsigned*)((const char*)(gbase) + (voff)[_i]), (PG8_LAS unsigned*)(lds + (bufoff) + ldsw + _i * 8192), 16, 0, 0); } while (0)
; #define PG8_LDA(dst, b, h) do { _Pragma("unroll") for (int m = 0; m < 4; ++m) _Pragma("unroll") for (int k = 0; k < 2; ++k) dst[m][k] = *(const PG8_LAS bf16x8*)(lds + PG8_SA(b, h) + aoff + m * 2048 + k * 1024); } while (0)
; #define PG8_LDB(dst, b, h) do { _Pragma("unroll") for (int n = 0; n < 2; ++n) _Pragma("unroll") for (int k = 0; k < 2; ++k) dst[n][k] = *(const PG8_LAS bf16x8*)(lds + PG8_SB(b, h) + boff + n * 2048 + k * 1024); } while (0)
; #define PG8_MMA(ai, bj, At, Bt) do { __builtin_amdgcn_s_setprio(1); _Pragma("unroll") for (int m = 0; m < 4; ++m) _Pragma("unroll") for (int n = 0; n < 2; ++n) _Pragma("unroll") for (int k = 0; k < 2; ++k) \
;         acc[ai][bj][m][n] = __builtin_amdgcn_mfma_f32_16x16x32_bf16(Bt[n][k], At[m][k], acc[ai][bj][m][n], 0, 0, 0); __builtin_amdgcn_s_setprio(0); } while (0)
; #define PG8_WAIT_V(n) asm volatile("s_waitcnt vmcnt(" #n ")" ::: "memory")
; #define PG8_WAIT_L(n) asm volatile("s_waitcnt lgkmcnt(" #n ")" ::: "memory")
; #define PG8_BAR __builtin_amdgcn_s_barrier()
; #define PG8_SCHED __builtin_amdgcn_sched_barrier(0)
; template <class Epi, class Sched, bool ALIGN_EPI = false, bool SP2 = false>
; __device__ __forceinline__ void gemm_phase(PG8_LAS unsigned char* lds, const Gemm g, const Sched& S, const Epi& E) {
;     ...
;             PG8_WAIT_V(8); PG8_WAIT_L(0); PG8_BAR; PG8_MMA(1, 0, At, B0); PG8_MMA(1, 1, At, B1); PG8_BAR; PG8_SCHED;
;             PG8_LDB(B0, 1, 0); PG8_LDB(B1, 1, 1); PG8_SCHED; PG8_LDA(At, 1, 0); PG8_STAGE(PG8_SA(0, 1), a2 + hstep, voffA);
;             PG8_WAIT_V(8); PG8_WAIT_L(0); PG8_BAR; PG8_MMA(0, 0, At, B0); PG8_MMA(0, 1, At, B1); PG8_BAR; PG8_SCHED;
	s_setprio 1
	s_waitcnt lgkmcnt(0)
	v_mfma_f32_16x16x32_bf16 v[62:65], v[152:155], v[194:197], v[62:65]
	v_mfma_f32_16x16x32_bf16 v[58:61], v[160:163], v[194:197], v[58:61]
	v_mfma_f32_16x16x32_bf16 v[54:57], v[152:155], v[202:205], v[54:57]
	v_mfma_f32_16x16x32_bf16 v[46:49], v[160:163], v[202:205], v[46:49]
	v_mfma_f32_16x16x32_bf16 v[38:41], v[152:155], v[210:213], v[38:41]
	v_mfma_f32_16x16x32_bf16 v[30:33], v[160:163], v[210:213], v[30:33]
	v_mfma_f32_16x16x32_bf16 v[22:25], v[152:155], v[218:221], v[22:25]
	v_mfma_f32_16x16x32_bf16 v[14:17], v[160:163], v[218:221], v[14:17]
	v_mfma_f32_16x16x32_bf16 v[62:65], v[156:159], v[198:201], v[62:65]
	v_mfma_f32_16x16x32_bf16 v[58:61], v[174:177], v[198:201], v[58:61]
	v_mfma_f32_16x16x32_bf16 v[54:57], v[156:159], v[206:209], v[54:57]
	v_mfma_f32_16x16x32_bf16 v[46:49], v[174:177], v[206:209], v[46:49]
	v_mfma_f32_16x16x32_bf16 v[38:41], v[156:159], v[214:217], v[38:41]
	v_mfma_f32_16x16x32_bf16 v[30:33], v[174:177], v[214:217], v[30:33]
	v_mfma_f32_16x16x32_bf16 v[22:25], v[156:159], v[222:225], v[22:25]
	v_mfma_f32_16x16x32_bf16 v[14:17], v[174:177], v[222:225], v[14:17]
	s_setprio 0
	s_setprio 1
	v_mfma_f32_16x16x32_bf16 v[50:53], v[178:181], v[194:197], v[50:53]
	v_mfma_f32_16x16x32_bf16 v[42:45], v[186:189], v[194:197], v[42:45]
	v_mfma_f32_16x16x32_bf16 v[34:37], v[178:181], v[202:205], v[34:37]
	v_mfma_f32_16x16x32_bf16 v[26:29], v[186:189], v[202:205], v[26:29]
	v_mfma_f32_16x16x32_bf16 v[18:21], v[178:181], v[210:213], v[18:21]
	v_mfma_f32_16x16x32_bf16 v[10:13], v[186:189], v[210:213], v[10:13]
	v_mfma_f32_16x16x32_bf16 v[6:9], v[178:181], v[218:221], v[6:9]
	v_mfma_f32_16x16x32_bf16 v[2:5], v[186:189], v[218:221], v[2:5]
	v_mfma_f32_16x16x32_bf16 v[50:53], v[182:185], v[198:201], v[50:53]
	v_mfma_f32_16x16x32_bf16 v[42:45], v[190:193], v[198:201], v[42:45]
	v_mfma_f32_16x16x32_bf16 v[34:37], v[182:185], v[206:209], v[34:37]
	v_mfma_f32_16x16x32_bf16 v[26:29], v[190:193], v[206:209], v[26:29]
	v_mfma_f32_16x16x32_bf16 v[18:21], v[182:185], v[214:217], v[18:21]
	s_setprio 2
	s_barrier
	v_mfma_f32_16x16x32_bf16 v[10:13], v[190:193], v[214:217], v[10:13]
	v_mfma_f32_16x16x32_bf16 v[6:9], v[182:185], v[222:225], v[6:9]
	v_mfma_f32_16x16x32_bf16 v[2:5], v[190:193], v[222:225], v[2:5]
	s_setprio 0
	s_add_i32 s64, 0, 0x18000
	v_add_u32_e32 v173, s64, v149
	s_add_i32 s65, 0, 0x1c000
	ds_read_b128 v[152:155], v173
	ds_read_b128 v[156:159], v173 offset:1024
	ds_read_b128 v[160:163], v173 offset:2048
	ds_read_b128 v[174:177], v173 offset:3072
	v_add_u32_e32 v173, s65, v149
	ds_read_b128 v[178:181], v173
	ds_read_b128 v[182:185], v173 offset:1024
	ds_read_b128 v[186:189], v173 offset:2048
	ds_read_b128 v[190:193], v173 offset:3072
	s_add_u32 s48, s48, 0x40000
	s_addc_u32 s49, s49, 0
	s_mov_b32 m0, s54
	v_lshl_add_u64 v[232:233], s[48:49], 0, v[140:141]
	ds_read_b128 v[194:197], v151 offset:32768
	ds_read_b128 v[198:201], v151 offset:33792
	ds_read_b128 v[202:205], v151 offset:34816
	ds_read_b128 v[206:209], v151 offset:35840
	ds_read_b128 v[210:213], v151 offset:36864
	ds_read_b128 v[214:217], v151 offset:37888
	ds_read_b128 v[218:221], v151 offset:38912
	ds_read_b128 v[222:225], v151 offset:39936
	global_load_lds_dwordx4 v[232:233], off
	v_lshl_add_u64 v[232:233], s[48:49], 0, v[138:139]
	s_mov_b32 m0, s55
	s_nop 0
	global_load_lds_dwordx4 v[232:233], off
	s_waitcnt vmcnt(8)
	s_waitcnt lgkmcnt(0)
	s_barrier
	s_setprio 1
	s_waitcnt lgkmcnt(0)
	v_mfma_f32_16x16x32_bf16 v[126:129], v[152:155], v[194:197], v[126:129]
	v_mfma_f32_16x16x32_bf16 v[122:125], v[160:163], v[194:197], v[122:125]
	v_mfma_f32_16x16x32_bf16 v[118:121], v[152:155], v[202:205], v[118:121]
	v_mfma_f32_16x16x32_bf16 v[110:113], v[160:163], v[202:205], v[110:113]
	v_mfma_f32_16x16x32_bf16 v[102:105], v[152:155], v[210:213], v[102:105]
	v_mfma_f32_16x16x32_bf16 v[94:97], v[160:163], v[210:213], v[94:97]
	v_mfma_f32_16x16x32_bf16 v[86:89], v[152:155], v[218:221], v[86:89]
	v_mfma_f32_16x16x32_bf16 v[78:81], v[160:163], v[218:221], v[78:81]
	v_mfma_f32_16x16x32_bf16 v[126:129], v[156:159], v[198:201], v[126:129]
	v_mfma_f32_16x16x32_bf16 v[122:125], v[174:177], v[198:201], v[122:125]
	v_mfma_f32_16x16x32_bf16 v[118:121], v[156:159], v[206:209], v[118:121]
	v_mfma_f32_16x16x32_bf16 v[110:113], v[174:177], v[206:209], v[110:113]
	v_mfma_f32_16x16x32_bf16 v[102:105], v[156:159], v[214:217], v[102:105]
	v_mfma_f32_16x16x32_bf16 v[94:97], v[174:177], v[214:217], v[94:97]
	v_mfma_f32_16x16x32_bf16 v[86:89], v[156:159], v[222:225], v[86:89]
	v_mfma_f32_16x16x32_bf16 v[78:81], v[174:177], v[222:225], v[78:81]
	s_setprio 0
	s_setprio 1
	v_mfma_f32_16x16x32_bf16 v[114:117], v[178:181], v[194:197], v[114:117]
	v_mfma_f32_16x16x32_bf16 v[106:109], v[186:189], v[194:197], v[106:109]
	v_mfma_f32_16x16x32_bf16 v[98:101], v[178:181], v[202:205], v[98:101]
	v_mfma_f32_16x16x32_bf16 v[90:93], v[186:189], v[202:205], v[90:93]
	v_mfma_f32_16x16x32_bf16 v[82:85], v[178:181], v[210:213], v[82:85]
	v_mfma_f32_16x16x32_bf16 v[74:77], v[186:189], v[210:213], v[74:77]
	v_mfma_f32_16x16x32_bf16 v[70:73], v[178:181], v[218:221], v[70:73]
	v_mfma_f32_16x16x32_bf16 v[66:69], v[186:189], v[218:221], v[66:69]
	v_mfma_f32_16x16x32_bf16 v[114:117], v[182:185], v[198:201], v[114:117]
	v_mfma_f32_16x16x32_bf16 v[106:109], v[190:193], v[198:201], v[106:109]
	v_mfma_f32_16x16x32_bf16 v[98:101], v[182:185], v[206:209], v[98:101]
	v_mfma_f32_16x16x32_bf16 v[90:93], v[190:193], v[206:209], v[90:93]
	v_mfma_f32_16x16x32_bf16 v[82:85], v[182:185], v[214:217], v[82:85]
	s_setprio 2
	s_barrier
; #define PG8_STAGE(bufoff, gbase, voff) do { _Pragma("unroll") for (int _i = 0; _i < 2; ++_i) \
;         __builtin_amdgcn_global_load_lds((const unsigned*)((const char*)(gbase) + (voff)[_i]), (PG8_LAS unsigned*)(lds + (bufoff) + ldsw + _i * 8192), 16, 0, 0); } while (0)
; #define PG8_LDA(dst, b, h) do { _Pragma("unroll") for (int m = 0; m < 4; ++m) _Pragma("unroll") for (int k = 0; k < 2; ++k) dst[m][k] = *(const PG8_LAS bf16x8*)(lds + PG8_SA(b, h) + aoff + m * 2048 + k * 1024); } while (0)
; #define PG8_MMA(ai, bj, At, Bt) do { __builtin_amdgcn_s_setprio(1); _Pragma("unroll") for (int m = 0; m < 4; ++m) _Pragma("unroll") for (int n = 0; n < 2; ++n) _Pragma("unroll") for (int k = 0; k < 2; ++k) \
;         acc[ai][bj][m][n] = __builtin_amdgcn_mfma_f32_16x16x32_bf16(Bt[n][k], At[m][k], acc[ai][bj][m][n], 0, 0, 0); __builtin_amdgcn_s_setprio(0); } while (0)
; #define PG8_WAIT_V(n) asm volatile("s_waitcnt vmcnt(" #n ")" ::: "memory")
; #define PG8_WAIT_L(n) asm volatile("s_waitcnt lgkmcnt(" #n ")" ::: "memory")
; #define PG8_BAR __builtin_amdgcn_s_barrier()
; #define PG8_SCHED __builtin_amdgcn_sched_barrier(0)
; template <class Epi, class Sched, bool ALIGN_EPI = false, bool SP2 = false>
; __device__ __forceinline__ void gemm_phase(PG8_LAS unsigned char* lds, const Gemm g, const Sched& S, const Epi& E) {
;     ...
;             PG8_LDA(At, 1, 1); PG8_STAGE(PG8_SB(1, 0), b3, voffB); PG8_STAGE(PG8_SB(1, 1), b3 + hstep, voffB); PG8_STAGE(PG8_SA(1, 0), a3, voffA);
;             PG8_WAIT_V(8); PG8_WAIT_L(0); PG8_BAR; PG8_MMA(1, 0, At, B0); PG8_MMA(1, 1, At, B1); PG8_BAR; PG8_SCHED;
;     ...
;         if constexpr (ALIGN_EPI) { if (wr == 0) PG8_BAR; }
	v_mfma_f32_16x16x32_bf16 v[74:77], v[190:193], v[214:217], v[74:77]
	v_mfma_f32_16x16x32_bf16 v[70:73], v[182:185], v[222:225], v[70:73]
	v_mfma_f32_16x16x32_bf16 v[66:69], v[190:193], v[222:225], v[66:69]
	s_setprio 0
	s_add_i32 s48, s64, s34
	v_lshl_add_u64 v[146:147], v[146:147], 0, s[96:97]
	s_mov_b32 m0, s48
	ds_read_b128 v[194:197], v151 offset:49152
	ds_read_b128 v[198:201], v151 offset:50176
	ds_read_b128 v[202:205], v151 offset:51200
	ds_read_b128 v[206:209], v151 offset:52224
	ds_read_b128 v[210:213], v151 offset:53248
	ds_read_b128 v[214:217], v151 offset:54272
	ds_read_b128 v[218:221], v151 offset:55296
	ds_read_b128 v[222:225], v151 offset:56320
	global_load_lds_dwordx4 v[146:147], off
	s_add_i32 m0, s48, 0x2000
	s_add_u32 s46, s46, 0x40080
	v_lshl_add_u64 v[146:147], v[226:227], 0, s[96:97]
	s_addc_u32 s47, s47, 0
	s_add_i32 s48, s65, s34
	global_load_lds_dwordx4 v[146:147], off
	v_lshl_add_u64 v[146:147], s[46:47], 0, v[130:131]
	s_mov_b32 m0, s48
	s_nop 0
	global_load_lds_dwordx4 v[146:147], off
	v_lshl_add_u64 v[146:147], s[46:47], 0, v[136:137]
	s_add_i32 m0, s48, 0x2000
	s_nop 0
	global_load_lds_dwordx4 v[146:147], off
	v_lshl_add_u64 v[146:147], v[228:229], 0, s[96:97]
	s_mov_b32 m0, s56
	s_nop 0
	global_load_lds_dwordx4 v[146:147], off
	v_lshl_add_u64 v[146:147], v[230:231], 0, s[96:97]
	s_mov_b32 m0, s57
	s_nop 0
	global_load_lds_dwordx4 v[146:147], off
	s_waitcnt vmcnt(8)
	s_waitcnt lgkmcnt(0)
	s_barrier
	s_setprio 1
	s_waitcnt lgkmcnt(0)
	v_mfma_f32_16x16x32_bf16 v[62:65], v[152:155], v[194:197], v[62:65]
	v_mfma_f32_16x16x32_bf16 v[58:61], v[160:163], v[194:197], v[58:61]
	v_mfma_f32_16x16x32_bf16 v[54:57], v[152:155], v[202:205], v[54:57]
	v_mfma_f32_16x16x32_bf16 v[46:49], v[160:163], v[202:205], v[46:49]
	v_mfma_f32_16x16x32_bf16 v[38:41], v[152:155], v[210:213], v[38:41]
	v_mfma_f32_16x16x32_bf16 v[30:33], v[160:163], v[210:213], v[30:33]
	v_mfma_f32_16x16x32_bf16 v[22:25], v[152:155], v[218:221], v[22:25]
	v_mfma_f32_16x16x32_bf16 v[14:17], v[160:163], v[218:221], v[14:17]
	v_mfma_f32_16x16x32_bf16 v[62:65], v[156:159], v[198:201], v[62:65]
	v_mfma_f32_16x16x32_bf16 v[58:61], v[174:177], v[198:201], v[58:61]
	v_mfma_f32_16x16x32_bf16 v[54:57], v[156:159], v[206:209], v[54:57]
	v_mfma_f32_16x16x32_bf16 v[46:49], v[174:177], v[206:209], v[46:49]
	v_mfma_f32_16x16x32_bf16 v[38:41], v[156:159], v[214:217], v[38:41]
	v_mfma_f32_16x16x32_bf16 v[30:33], v[174:177], v[214:217], v[30:33]
	v_mfma_f32_16x16x32_bf16 v[22:25], v[156:159], v[222:225], v[22:25]
	v_mfma_f32_16x16x32_bf16 v[14:17], v[174:177], v[222:225], v[14:17]
	s_setprio 0
	s_setprio 1
	v_mfma_f32_16x16x32_bf16 v[50:53], v[178:181], v[194:197], v[50:53]
	v_mfma_f32_16x16x32_bf16 v[42:45], v[186:189], v[194:197], v[42:45]
	v_mfma_f32_16x16x32_bf16 v[34:37], v[178:181], v[202:205], v[34:37]
	v_mfma_f32_16x16x32_bf16 v[26:29], v[186:189], v[202:205], v[26:29]
	v_mfma_f32_16x16x32_bf16 v[18:21], v[178:181], v[210:213], v[18:21]
	v_mfma_f32_16x16x32_bf16 v[10:13], v[186:189], v[210:213], v[10:13]
	v_mfma_f32_16x16x32_bf16 v[6:9], v[178:181], v[218:221], v[6:9]
	v_mfma_f32_16x16x32_bf16 v[2:5], v[186:189], v[218:221], v[2:5]
	v_mfma_f32_16x16x32_bf16 v[50:53], v[182:185], v[198:201], v[50:53]
	v_mfma_f32_16x16x32_bf16 v[42:45], v[190:193], v[198:201], v[42:45]
	v_mfma_f32_16x16x32_bf16 v[34:37], v[182:185], v[206:209], v[34:37]
	v_mfma_f32_16x16x32_bf16 v[26:29], v[190:193], v[206:209], v[26:29]
	v_mfma_f32_16x16x32_bf16 v[18:21], v[182:185], v[214:217], v[18:21]
	s_setprio 2
	s_barrier
	v_mfma_f32_16x16x32_bf16 v[10:13], v[190:193], v[214:217], v[10:13]
	v_mfma_f32_16x16x32_bf16 v[6:9], v[182:185], v[222:225], v[6:9]
	v_mfma_f32_16x16x32_bf16 v[2:5], v[190:193], v[222:225], v[2:5]
	s_setprio 0
	s_add_i32 s63, s63, 2
	s_add_u32 s44, s44, 0x100
	s_addc_u32 s45, s45, 0
	s_add_u32 s61, s61, 0x100
	s_addc_u32 s62, s62, 0
	s_cmp_gt_u32 s63, 13
	s_cbranch_scc0 .LBB0_121
	s_and_b64 vcc, exec, s[6:7]
	s_cbranch_vccz .LBB0_124
	s_barrier

; #define PG8_STAGE(bufoff, gbase, voff) do { _Pragma("unroll") for (int _i = 0; _i < 2; ++_i) \
;         __builtin_amdgcn_global_load_lds((const unsigned*)((const char*)(gbase) + (voff)[_i]), (PG8_LAS unsigned*)(lds + (bufoff) + ldsw + _i * 8192), 16, 0, 0); } while (0)
; #define PG8_LDA(dst, b, h) do { _Pragma("unroll") for (int m = 0; m < 4; ++m) _Pragma("unroll") for (int k = 0; k < 2; ++k) dst[m][k] = *(const PG8_LAS bf16x8*)(lds + PG8_SA(b, h) + aoff + m * 2048 + k * 1024); } while (0)
; #define PG8_LDB(dst, b, h) do { _Pragma("unroll") for (int n = 0; n < 2; ++n) _Pragma("unroll") for (int k = 0; k < 2; ++k) dst[n][k] = *(const PG8_LAS bf16x8*)(lds + PG8_SB(b, h) + boff + n * 2048 + k * 1024); } while (0)
; #define PG8_MMA(ai, bj, At, Bt) do { __builtin_amdgcn_s_setprio(1); _Pragma("unroll") for (int m = 0; m < 4; ++m) _Pragma("unroll") for (int n = 0; n < 2; ++n) _Pragma("unroll") for (int k = 0; k < 2; ++k) \
;         acc[ai][bj][m][n] = __builtin_amdgcn_mfma_f32_16x16x32_bf16(Bt[n][k], At[m][k], acc[ai][bj][m][n], 0, 0, 0); __builtin_amdgcn_s_setprio(0); } while (0)
; #define PG8_WAIT_V(n) asm volatile("s_waitcnt vmcnt(" #n ")" ::: "memory")
; #define PG8_WAIT_L(n) asm volatile("s_waitcnt lgkmcnt(" #n ")" ::: "memory")
; #define PG8_BAR __builtin_amdgcn_s_barrier()
; #define PG8_SCHED __builtin_amdgcn_sched_barrier(0)
; template <class Epi, class Sched, bool ALIGN_EPI = false, bool SP2 = false>
; __device__ __forceinline__ void gemm_phase(PG8_LAS unsigned char* lds, const Gemm g, const Sched& S, const Epi& E) {
;     ...
;             PG8_LDB(B0, 0, 0); PG8_LDB(B1, 0, 1); PG8_SCHED; PG8_LDA(At, 0, 0); PG8_STAGE(PG8_SA(1, 1), a1 + hstep, voffA);
;             PG8_WAIT_V(8); PG8_WAIT_L(0); PG8_BAR; PG8_MMA(0, 0, At, B0); PG8_MMA(0, 1, At, B1); PG8_BAR; PG8_SCHED;
;             PG8_LDA(At, 0, 1); PG8_STAGE(PG8_SB(0, 0), b2, voffB); PG8_STAGE(PG8_SB(0, 1), b2 + hstep, voffB); PG8_STAGE(PG8_SA(0, 0), a2, voffA);
.LBB0_811:
	ds_read_b128 v[130:133], v159
	ds_read_b128 v[152:155], v159 offset:1024
	ds_read_b128 v[166:169], v159 offset:2048
	ds_read_b128 v[170:173], v159 offset:3072
	ds_read_b128 v[174:177], v160
	ds_read_b128 v[178:181], v160 offset:1024
	ds_read_b128 v[182:185], v160 offset:2048
	ds_read_b128 v[186:189], v160 offset:3072
	s_add_u32 s42, s4, 0xfffc0080
	s_addc_u32 s43, s5, -1
	s_cmp_eq_u32 s47, 12
	s_cselect_b32 s45, s35, s43
	s_cselect_b32 s44, s34, s42
	s_cselect_b32 s43, s6, s46
	s_cselect_b32 s42, s23, s25
	v_lshl_add_u64 v[162:163], s[4:5], 0, v[144:145]
	s_add_i32 m0, s39, 0xc000
	ds_read_b128 v[190:193], v161
	ds_read_b128 v[194:197], v161 offset:1024
	ds_read_b128 v[198:201], v161 offset:2048
	ds_read_b128 v[202:205], v161 offset:3072
	ds_read_b128 v[206:209], v161 offset:4096
	ds_read_b128 v[210:213], v161 offset:5120
	ds_read_b128 v[214:217], v161 offset:6144
	ds_read_b128 v[218:221], v161 offset:7168
	global_load_lds_dwordx4 v[162:163], off
	v_lshl_add_u64 v[162:163], s[4:5], 0, v[146:147]
	s_add_i32 m0, s39, 0xe000
	s_nop 0
	global_load_lds_dwordx4 v[162:163], off
	s_waitcnt vmcnt(8)
	s_waitcnt lgkmcnt(0)
	s_barrier
	s_setprio 1
	s_waitcnt lgkmcnt(0)
	v_mfma_f32_16x16x32_bf16 v[126:129], v[130:133], v[190:193], v[126:129]
	v_mfma_f32_16x16x32_bf16 v[122:125], v[166:169], v[190:193], v[122:125]
	v_mfma_f32_16x16x32_bf16 v[110:113], v[130:133], v[198:201], v[110:113]
	v_mfma_f32_16x16x32_bf16 v[106:109], v[166:169], v[198:201], v[106:109]
	v_mfma_f32_16x16x32_bf16 v[94:97], v[130:133], v[206:209], v[94:97]
	v_mfma_f32_16x16x32_bf16 v[90:93], v[166:169], v[206:209], v[90:93]
	v_mfma_f32_16x16x32_bf16 v[78:81], v[130:133], v[214:217], v[78:81]
	v_mfma_f32_16x16x32_bf16 v[74:77], v[166:169], v[214:217], v[74:77]
	v_mfma_f32_16x16x32_bf16 v[126:129], v[152:155], v[194:197], v[126:129]
	v_mfma_f32_16x16x32_bf16 v[122:125], v[170:173], v[194:197], v[122:125]
	v_mfma_f32_16x16x32_bf16 v[110:113], v[152:155], v[202:205], v[110:113]
	v_mfma_f32_16x16x32_bf16 v[106:109], v[170:173], v[202:205], v[106:109]
	v_mfma_f32_16x16x32_bf16 v[94:97], v[152:155], v[210:213], v[94:97]
	v_mfma_f32_16x16x32_bf16 v[90:93], v[170:173], v[210:213], v[90:93]
	v_mfma_f32_16x16x32_bf16 v[78:81], v[152:155], v[218:221], v[78:81]
	v_mfma_f32_16x16x32_bf16 v[74:77], v[170:173], v[218:221], v[74:77]
	s_setprio 0
	s_setprio 1
	v_mfma_f32_16x16x32_bf16 v[118:121], v[174:177], v[190:193], v[118:121]
	v_mfma_f32_16x16x32_bf16 v[114:117], v[182:185], v[190:193], v[114:117]
	v_mfma_f32_16x16x32_bf16 v[102:105], v[174:177], v[198:201], v[102:105]
	v_mfma_f32_16x16x32_bf16 v[98:101], v[182:185], v[198:201], v[98:101]
	v_mfma_f32_16x16x32_bf16 v[86:89], v[174:177], v[206:209], v[86:89]
	v_mfma_f32_16x16x32_bf16 v[82:85], v[182:185], v[206:209], v[82:85]
	v_mfma_f32_16x16x32_bf16 v[70:73], v[174:177], v[214:217], v[70:73]
	v_mfma_f32_16x16x32_bf16 v[66:69], v[182:185], v[214:217], v[66:69]
	v_mfma_f32_16x16x32_bf16 v[118:121], v[178:181], v[194:197], v[118:121]
	v_mfma_f32_16x16x32_bf16 v[114:117], v[186:189], v[194:197], v[114:117]
	v_mfma_f32_16x16x32_bf16 v[102:105], v[178:181], v[202:205], v[102:105]
	v_mfma_f32_16x16x32_bf16 v[98:101], v[186:189], v[202:205], v[98:101]
	v_mfma_f32_16x16x32_bf16 v[86:89], v[178:181], v[210:213], v[86:89]
	s_setprio 2
	s_barrier
	v_mfma_f32_16x16x32_bf16 v[82:85], v[186:189], v[210:213], v[82:85]
	v_mfma_f32_16x16x32_bf16 v[70:73], v[178:181], v[218:221], v[70:73]
	v_mfma_f32_16x16x32_bf16 v[66:69], v[186:189], v[218:221], v[66:69]
	s_setprio 0
	s_add_i32 s61, s54, s33
	v_lshl_add_u64 v[162:163], s[42:43], 0, v[136:137]
	s_mov_b32 m0, s61
	ds_read_b128 v[190:193], v161 offset:16384
	ds_read_b128 v[194:197], v161 offset:17408
	ds_read_b128 v[198:201], v161 offset:18432
	ds_read_b128 v[202:205], v161 offset:19456
	ds_read_b128 v[206:209], v161 offset:20480
	ds_read_b128 v[210:213], v161 offset:21504
	ds_read_b128 v[214:217], v161 offset:22528
	ds_read_b128 v[218:221], v161 offset:23552
	global_load_lds_dwordx4 v[162:163], off
	s_add_i32 m0, s61, 0x2000
	s_add_u32 s62, s42, 0x40000
	v_lshl_add_u64 v[222:223], s[42:43], 0, v[140:141]
	s_addc_u32 s63, s43, 0
	s_add_i32 s61, s55, s33
	global_load_lds_dwordx4 v[222:223], off
	v_lshl_add_u64 v[224:225], s[62:63], 0, v[136:137]
	s_mov_b32 m0, s61
	v_lshl_add_u64 v[226:227], s[44:45], 0, v[138:139]
	global_load_lds_dwordx4 v[224:225], off
	v_lshl_add_u64 v[224:225], s[62:63], 0, v[140:141]
	s_add_i32 m0, s61, 0x2000
	s_nop 0
	global_load_lds_dwordx4 v[224:225], off
	v_lshl_add_u64 v[224:225], s[44:45], 0, v[134:135]
	s_mov_b32 m0, s39
	s_nop 0
	global_load_lds_dwordx4 v[224:225], off
	s_mov_b32 m0, s49
	s_nop 0
	global_load_lds_dwordx4 v[226:227], off
	s_waitcnt vmcnt(8)
	s_waitcnt lgkmcnt(0)
	s_barrier
; #define PG8_STAGE(bufoff, gbase, voff) do { _Pragma("unroll") for (int _i = 0; _i < 2; ++_i) \
;         __builtin_amdgcn_global_load_lds((const unsigned*)((const char*)(gbase) + (voff)[_i]), (PG8_LAS unsigned*)(lds + (bufoff) + ldsw + _i * 8192), 16, 0, 0); } while (0)
; #define PG8_LDA(dst, b, h) do { _Pragma("unroll") for (int m = 0; m < 4; ++m) _Pragma("unroll") for (int k = 0; k < 2; ++k) dst[m][k] = *(const PG8_LAS bf16x8*)(lds + PG8_SA(b, h) + aoff + m * 2048 + k * 1024); } while (0)
; #define PG8_LDB(dst, b, h) do { _Pragma("unroll") for (int n = 0; n < 2; ++n) _Pragma("unroll") for (int k = 0; k < 2; ++k) dst[n][k] = *(const PG8_LAS bf16x8*)(lds + PG8_SB(b, h) + boff + n * 2048 + k * 1024); } while (0)
; #define PG8_MMA(ai, bj, At, Bt) do { __builtin_amdgcn_s_setprio(1); _Pragma("unroll") for (int m = 0; m < 4; ++m) _Pragma("unroll") for (int n = 0; n < 2; ++n) _Pragma("unroll") for (int k = 0; k < 2; ++k) \
;         acc[ai][bj][m][n] = __builtin_amdgcn_mfma_f32_16x16x32_bf16(Bt[n][k], At[m][k], acc[ai][bj][m][n], 0, 0, 0); __builtin_amdgcn_s_setprio(0); } while (0)
; #define PG8_WAIT_V(n) asm volatile("s_waitcnt vmcnt(" #n ")" ::: "memory")
; #define PG8_WAIT_L(n) asm volatile("s_waitcnt lgkmcnt(" #n ")" ::: "memory")
; #define PG8_BAR __builtin_amdgcn_s_barrier()
; #define PG8_SCHED __builtin_amdgcn_sched_barrier(0)
; template <class Epi, class Sched, bool ALIGN_EPI = false, bool SP2 = false>
; __device__ __forceinline__ void gemm_phase(PG8_LAS unsigned char* lds, const Gemm g, const Sched& S, const Epi& E) {
;     ...
;             PG8_WAIT_V(8); PG8_WAIT_L(0); PG8_BAR; PG8_MMA(1, 0, At, B0); PG8_MMA(1, 1, At, B1); PG8_BAR; PG8_SCHED;
;             PG8_LDB(B0, 1, 0); PG8_LDB(B1, 1, 1); PG8_SCHED; PG8_LDA(At, 1, 0); PG8_STAGE(PG8_SA(0, 1), a2 + hstep, voffA);
;             PG8_WAIT_V(8); PG8_WAIT_L(0); PG8_BAR; PG8_MMA(0, 0, At, B0); PG8_MMA(0, 1, At, B1); PG8_BAR; PG8_SCHED;
	s_setprio 1
	s_waitcnt lgkmcnt(0)
	v_mfma_f32_16x16x32_bf16 v[62:65], v[130:133], v[190:193], v[62:65]
	v_mfma_f32_16x16x32_bf16 v[58:61], v[166:169], v[190:193], v[58:61]
	v_mfma_f32_16x16x32_bf16 v[46:49], v[130:133], v[198:201], v[46:49]
	v_mfma_f32_16x16x32_bf16 v[42:45], v[166:169], v[198:201], v[42:45]
	v_mfma_f32_16x16x32_bf16 v[30:33], v[130:133], v[206:209], v[30:33]
	v_mfma_f32_16x16x32_bf16 v[26:29], v[166:169], v[206:209], v[26:29]
	v_mfma_f32_16x16x32_bf16 v[14:17], v[130:133], v[214:217], v[14:17]
	v_mfma_f32_16x16x32_bf16 v[10:13], v[166:169], v[214:217], v[10:13]
	v_mfma_f32_16x16x32_bf16 v[62:65], v[152:155], v[194:197], v[62:65]
	v_mfma_f32_16x16x32_bf16 v[58:61], v[170:173], v[194:197], v[58:61]
	v_mfma_f32_16x16x32_bf16 v[46:49], v[152:155], v[202:205], v[46:49]
	v_mfma_f32_16x16x32_bf16 v[42:45], v[170:173], v[202:205], v[42:45]
	v_mfma_f32_16x16x32_bf16 v[30:33], v[152:155], v[210:213], v[30:33]
	v_mfma_f32_16x16x32_bf16 v[26:29], v[170:173], v[210:213], v[26:29]
	v_mfma_f32_16x16x32_bf16 v[14:17], v[152:155], v[218:221], v[14:17]
	v_mfma_f32_16x16x32_bf16 v[10:13], v[170:173], v[218:221], v[10:13]
	s_setprio 0
	s_setprio 1
	v_mfma_f32_16x16x32_bf16 v[54:57], v[174:177], v[190:193], v[54:57]
	v_mfma_f32_16x16x32_bf16 v[50:53], v[182:185], v[190:193], v[50:53]
	v_mfma_f32_16x16x32_bf16 v[38:41], v[174:177], v[198:201], v[38:41]
	v_mfma_f32_16x16x32_bf16 v[34:37], v[182:185], v[198:201], v[34:37]
	v_mfma_f32_16x16x32_bf16 v[22:25], v[174:177], v[206:209], v[22:25]
	v_mfma_f32_16x16x32_bf16 v[18:21], v[182:185], v[206:209], v[18:21]
	v_mfma_f32_16x16x32_bf16 v[6:9], v[174:177], v[214:217], v[6:9]
	v_mfma_f32_16x16x32_bf16 v[2:5], v[182:185], v[214:217], v[2:5]
	v_mfma_f32_16x16x32_bf16 v[54:57], v[178:181], v[194:197], v[54:57]
	v_mfma_f32_16x16x32_bf16 v[50:53], v[186:189], v[194:197], v[50:53]
	v_mfma_f32_16x16x32_bf16 v[38:41], v[178:181], v[202:205], v[38:41]
	v_mfma_f32_16x16x32_bf16 v[34:37], v[186:189], v[202:205], v[34:37]
	v_mfma_f32_16x16x32_bf16 v[22:25], v[178:181], v[210:213], v[22:25]
	s_setprio 2
	s_barrier
	v_mfma_f32_16x16x32_bf16 v[18:21], v[186:189], v[210:213], v[18:21]
	v_mfma_f32_16x16x32_bf16 v[6:9], v[178:181], v[218:221], v[6:9]
	v_mfma_f32_16x16x32_bf16 v[2:5], v[186:189], v[218:221], v[2:5]
	s_setprio 0
	s_add_i32 s61, 0, 0x18000
	v_add_u32_e32 v142, s61, v157
	s_add_i32 s62, 0, 0x1c000
	ds_read_b128 v[130:133], v142
	ds_read_b128 v[152:155], v142 offset:1024
	ds_read_b128 v[166:169], v142 offset:2048
	ds_read_b128 v[170:173], v142 offset:3072
	v_add_u32_e32 v142, s62, v157
	ds_read_b128 v[174:177], v142
	ds_read_b128 v[178:181], v142 offset:1024
	ds_read_b128 v[182:185], v142 offset:2048
	ds_read_b128 v[186:189], v142 offset:3072
	s_add_u32 s44, s44, 0x40000
	s_addc_u32 s45, s45, 0
	s_mov_b32 m0, s50
	v_lshl_add_u64 v[228:229], s[44:45], 0, v[134:135]
	ds_read_b128 v[190:193], v161 offset:32768
	ds_read_b128 v[194:197], v161 offset:33792
	ds_read_b128 v[198:201], v161 offset:34816
	ds_read_b128 v[202:205], v161 offset:35840
	ds_read_b128 v[206:209], v161 offset:36864
	ds_read_b128 v[210:213], v161 offset:37888
	ds_read_b128 v[214:217], v161 offset:38912
	ds_read_b128 v[218:221], v161 offset:39936
	global_load_lds_dwordx4 v[228:229], off
	v_lshl_add_u64 v[228:229], s[44:45], 0, v[138:139]
	s_mov_b32 m0, s51
	s_nop 0
	global_load_lds_dwordx4 v[228:229], off
	s_waitcnt vmcnt(8)
	s_waitcnt lgkmcnt(0)
	s_barrier
	s_setprio 1
	s_waitcnt lgkmcnt(0)
	v_mfma_f32_16x16x32_bf16 v[126:129], v[130:133], v[190:193], v[126:129]
	v_mfma_f32_16x16x32_bf16 v[122:125], v[166:169], v[190:193], v[122:125]
	v_mfma_f32_16x16x32_bf16 v[110:113], v[130:133], v[198:201], v[110:113]
	v_mfma_f32_16x16x32_bf16 v[106:109], v[166:169], v[198:201], v[106:109]
	v_mfma_f32_16x16x32_bf16 v[94:97], v[130:133], v[206:209], v[94:97]
	v_mfma_f32_16x16x32_bf16 v[90:93], v[166:169], v[206:209], v[90:93]
	v_mfma_f32_16x16x32_bf16 v[78:81], v[130:133], v[214:217], v[78:81]
	v_mfma_f32_16x16x32_bf16 v[74:77], v[166:169], v[214:217], v[74:77]
	v_mfma_f32_16x16x32_bf16 v[126:129], v[152:155], v[194:197], v[126:129]
	v_mfma_f32_16x16x32_bf16 v[122:125], v[170:173], v[194:197], v[122:125]
	v_mfma_f32_16x16x32_bf16 v[110:113], v[152:155], v[202:205], v[110:113]
	v_mfma_f32_16x16x32_bf16 v[106:109], v[170:173], v[202:205], v[106:109]
	v_mfma_f32_16x16x32_bf16 v[94:97], v[152:155], v[210:213], v[94:97]
	v_mfma_f32_16x16x32_bf16 v[90:93], v[170:173], v[210:213], v[90:93]
	v_mfma_f32_16x16x32_bf16 v[78:81], v[152:155], v[218:221], v[78:81]
	v_mfma_f32_16x16x32_bf16 v[74:77], v[170:173], v[218:221], v[74:77]
	s_setprio 0
	s_setprio 1
	v_mfma_f32_16x16x32_bf16 v[118:121], v[174:177], v[190:193], v[118:121]
	v_mfma_f32_16x16x32_bf16 v[114:117], v[182:185], v[190:193], v[114:117]
	v_mfma_f32_16x16x32_bf16 v[102:105], v[174:177], v[198:201], v[102:105]
	v_mfma_f32_16x16x32_bf16 v[98:101], v[182:185], v[198:201], v[98:101]
	v_mfma_f32_16x16x32_bf16 v[86:89], v[174:177], v[206:209], v[86:89]
	v_mfma_f32_16x16x32_bf16 v[82:85], v[182:185], v[206:209], v[82:85]
	v_mfma_f32_16x16x32_bf16 v[70:73], v[174:177], v[214:217], v[70:73]
	v_mfma_f32_16x16x32_bf16 v[66:69], v[182:185], v[214:217], v[66:69]
	v_mfma_f32_16x16x32_bf16 v[118:121], v[178:181], v[194:197], v[118:121]
	v_mfma_f32_16x16x32_bf16 v[114:117], v[186:189], v[194:197], v[114:117]
	v_mfma_f32_16x16x32_bf16 v[102:105], v[178:181], v[202:205], v[102:105]
	v_mfma_f32_16x16x32_bf16 v[98:101], v[186:189], v[202:205], v[98:101]
	v_mfma_f32_16x16x32_bf16 v[86:89], v[178:181], v[210:213], v[86:89]
	s_setprio 2
	s_barrier
; #define PG8_STAGE(bufoff, gbase, voff) do { _Pragma("unroll") for (int _i = 0; _i < 2; ++_i) \
;         __builtin_amdgcn_global_load_lds((const unsigned*)((const char*)(gbase) + (voff)[_i]), (PG8_LAS unsigned*)(lds + (bufoff) + ldsw + _i * 8192), 16, 0, 0); } while (0)
; #define PG8_LDA(dst, b, h) do { _Pragma("unroll") for (int m = 0; m < 4; ++m) _Pragma("unroll") for (int k = 0; k < 2; ++k) dst[m][k] = *(const PG8_LAS bf16x8*)(lds + PG8_SA(b, h) + aoff + m * 2048 + k * 1024); } while (0)
; #define PG8_MMA(ai, bj, At, Bt) do { __builtin_amdgcn_s_setprio(1); _Pragma("unroll") for (int m = 0; m < 4; ++m) _Pragma("unroll") for (int n = 0; n < 2; ++n) _Pragma("unroll") for (int k = 0; k < 2; ++k) \
;         acc[ai][bj][m][n] = __builtin_amdgcn_mfma_f32_16x16x32_bf16(Bt[n][k], At[m][k], acc[ai][bj][m][n], 0, 0, 0); __builtin_amdgcn_s_setprio(0); } while (0)
; #define PG8_WAIT_V(n) asm volatile("s_waitcnt vmcnt(" #n ")" ::: "memory")
; #define PG8_WAIT_L(n) asm volatile("s_waitcnt lgkmcnt(" #n ")" ::: "memory")
; #define PG8_BAR __builtin_amdgcn_s_barrier()
; #define PG8_SCHED __builtin_amdgcn_sched_barrier(0)
; template <class Epi, class Sched, bool ALIGN_EPI = false, bool SP2 = false>
; __device__ __forceinline__ void gemm_phase(PG8_LAS unsigned char* lds, const Gemm g, const Sched& S, const Epi& E) {
;     ...
;             PG8_LDA(At, 1, 1); PG8_STAGE(PG8_SB(1, 0), b3, voffB); PG8_STAGE(PG8_SB(1, 1), b3 + hstep, voffB); PG8_STAGE(PG8_SA(1, 0), a3, voffA);
;             PG8_WAIT_V(8); PG8_WAIT_L(0); PG8_BAR; PG8_MMA(1, 0, At, B0); PG8_MMA(1, 1, At, B1); PG8_BAR; PG8_SCHED;
;     ...
;         if constexpr (ALIGN_EPI) { if (wr == 0) PG8_BAR; }
	v_mfma_f32_16x16x32_bf16 v[82:85], v[186:189], v[210:213], v[82:85]
	v_mfma_f32_16x16x32_bf16 v[70:73], v[178:181], v[218:221], v[70:73]
	v_mfma_f32_16x16x32_bf16 v[66:69], v[186:189], v[218:221], v[66:69]
	s_setprio 0
	s_add_i32 s44, s61, s33
	v_lshl_add_u64 v[162:163], v[162:163], 0, s[12:13]
	s_mov_b32 m0, s44
	ds_read_b128 v[190:193], v161 offset:49152
	ds_read_b128 v[194:197], v161 offset:50176
	ds_read_b128 v[198:201], v161 offset:51200
	ds_read_b128 v[202:205], v161 offset:52224
	ds_read_b128 v[206:209], v161 offset:53248
	ds_read_b128 v[210:213], v161 offset:54272
	ds_read_b128 v[214:217], v161 offset:55296
	ds_read_b128 v[218:221], v161 offset:56320
	global_load_lds_dwordx4 v[162:163], off
	s_add_i32 m0, s44, 0x2000
	s_add_u32 s42, s42, 0x40080
	v_lshl_add_u64 v[162:163], v[222:223], 0, s[12:13]
	s_addc_u32 s43, s43, 0
	s_add_i32 s44, s62, s33
	global_load_lds_dwordx4 v[162:163], off
	v_lshl_add_u64 v[162:163], s[42:43], 0, v[136:137]
	s_mov_b32 m0, s44
	s_nop 0
	global_load_lds_dwordx4 v[162:163], off
	v_lshl_add_u64 v[162:163], s[42:43], 0, v[140:141]
	s_add_i32 m0, s44, 0x2000
	s_nop 0
	global_load_lds_dwordx4 v[162:163], off
	v_lshl_add_u64 v[162:163], v[224:225], 0, s[12:13]
	s_mov_b32 m0, s52
	s_nop 0
	global_load_lds_dwordx4 v[162:163], off
	v_lshl_add_u64 v[162:163], v[226:227], 0, s[12:13]
	s_mov_b32 m0, s53
	s_nop 0
	global_load_lds_dwordx4 v[162:163], off
	s_waitcnt vmcnt(8)
	s_waitcnt lgkmcnt(0)
	s_barrier
	s_setprio 1
	s_waitcnt lgkmcnt(0)
	v_mfma_f32_16x16x32_bf16 v[62:65], v[130:133], v[190:193], v[62:65]
	v_mfma_f32_16x16x32_bf16 v[58:61], v[166:169], v[190:193], v[58:61]
	v_mfma_f32_16x16x32_bf16 v[46:49], v[130:133], v[198:201], v[46:49]
	v_mfma_f32_16x16x32_bf16 v[42:45], v[166:169], v[198:201], v[42:45]
	v_mfma_f32_16x16x32_bf16 v[30:33], v[130:133], v[206:209], v[30:33]
	v_mfma_f32_16x16x32_bf16 v[26:29], v[166:169], v[206:209], v[26:29]
	v_mfma_f32_16x16x32_bf16 v[14:17], v[130:133], v[214:217], v[14:17]
	v_mfma_f32_16x16x32_bf16 v[10:13], v[166:169], v[214:217], v[10:13]
	v_mfma_f32_16x16x32_bf16 v[62:65], v[152:155], v[194:197], v[62:65]
	v_mfma_f32_16x16x32_bf16 v[58:61], v[170:173], v[194:197], v[58:61]
	v_mfma_f32_16x16x32_bf16 v[46:49], v[152:155], v[202:205], v[46:49]
	v_mfma_f32_16x16x32_bf16 v[42:45], v[170:173], v[202:205], v[42:45]
	v_mfma_f32_16x16x32_bf16 v[30:33], v[152:155], v[210:213], v[30:33]
	v_mfma_f32_16x16x32_bf16 v[26:29], v[170:173], v[210:213], v[26:29]
	v_mfma_f32_16x16x32_bf16 v[14:17], v[152:155], v[218:221], v[14:17]
	v_mfma_f32_16x16x32_bf16 v[10:13], v[170:173], v[218:221], v[10:13]
	s_setprio 0
	s_setprio 1
	v_mfma_f32_16x16x32_bf16 v[54:57], v[174:177], v[190:193], v[54:57]
	v_mfma_f32_16x16x32_bf16 v[50:53], v[182:185], v[190:193], v[50:53]
	v_mfma_f32_16x16x32_bf16 v[38:41], v[174:177], v[198:201], v[38:41]
	v_mfma_f32_16x16x32_bf16 v[34:37], v[182:185], v[198:201], v[34:37]
	v_mfma_f32_16x16x32_bf16 v[22:25], v[174:177], v[206:209], v[22:25]
	v_mfma_f32_16x16x32_bf16 v[18:21], v[182:185], v[206:209], v[18:21]
	v_mfma_f32_16x16x32_bf16 v[6:9], v[174:177], v[214:217], v[6:9]
	v_mfma_f32_16x16x32_bf16 v[2:5], v[182:185], v[214:217], v[2:5]
	v_mfma_f32_16x16x32_bf16 v[54:57], v[178:181], v[194:197], v[54:57]
	v_mfma_f32_16x16x32_bf16 v[50:53], v[186:189], v[194:197], v[50:53]
	v_mfma_f32_16x16x32_bf16 v[38:41], v[178:181], v[202:205], v[38:41]
	v_mfma_f32_16x16x32_bf16 v[34:37], v[186:189], v[202:205], v[34:37]
	v_mfma_f32_16x16x32_bf16 v[22:25], v[178:181], v[210:213], v[22:25]
	s_setprio 2
	s_barrier
	v_mfma_f32_16x16x32_bf16 v[18:21], v[186:189], v[210:213], v[18:21]
	v_mfma_f32_16x16x32_bf16 v[6:9], v[178:181], v[218:221], v[6:9]
	v_mfma_f32_16x16x32_bf16 v[2:5], v[186:189], v[218:221], v[2:5]
	s_setprio 0
	s_add_i32 s47, s47, 2
	s_add_u32 s4, s4, 0x100
	s_addc_u32 s5, s5, 0
	s_add_u32 s25, s25, 0x100
	s_addc_u32 s46, s46, 0
	s_cmp_gt_u32 s47, 13
	s_cbranch_scc0 .LBB0_811
	s_and_b64 vcc, exec, s[14:15]
	s_cbranch_vccz .LBB0_814
	s_barrier

; #define PG8_STAGE(bufoff, gbase, voff) do { _Pragma("unroll") for (int _i = 0; _i < 2; ++_i) \
;         __builtin_amdgcn_global_load_lds((const unsigned*)((const char*)(gbase) + (voff)[_i]), (PG8_LAS unsigned*)(lds + (bufoff) + ldsw + _i * 8192), 16, 0, 0); } while (0)
; #define PG8_LDA(dst, b, h) do { _Pragma("unroll") for (int m = 0; m < 4; ++m) _Pragma("unroll") for (int k = 0; k < 2; ++k) dst[m][k] = *(const PG8_LAS bf16x8*)(lds + PG8_SA(b, h) + aoff + m * 2048 + k * 1024); } while (0)
; #define PG8_LDB(dst, b, h) do { _Pragma("unroll") for (int n = 0; n < 2; ++n) _Pragma("unroll") for (int k = 0; k < 2; ++k) dst[n][k] = *(const PG8_LAS bf16x8*)(lds + PG8_SB(b, h) + boff + n * 2048 + k * 1024); } while (0)
; #define PG8_MMA(ai, bj, At, Bt) do { __builtin_amdgcn_s_setprio(1); _Pragma("unroll") for (int m = 0; m < 4; ++m) _Pragma("unroll") for (int n = 0; n < 2; ++n) _Pragma("unroll") for (int k = 0; k < 2; ++k) \
;         acc[ai][bj][m][n] = __builtin_amdgcn_mfma_f32_16x16x32_bf16(Bt[n][k], At[m][k], acc[ai][bj][m][n], 0, 0, 0); __builtin_amdgcn_s_setprio(0); } while (0)
; #define PG8_WAIT_V(n) asm volatile("s_waitcnt vmcnt(" #n ")" ::: "memory")
; #define PG8_WAIT_L(n) asm volatile("s_waitcnt lgkmcnt(" #n ")" ::: "memory")
; #define PG8_BAR __builtin_amdgcn_s_barrier()
; #define PG8_SCHED __builtin_amdgcn_sched_barrier(0)
; template <class Epi, class Sched, bool ALIGN_EPI = false, bool SP2 = false>
; __device__ __forceinline__ void gemm_phase(PG8_LAS unsigned char* lds, const Gemm g, const Sched& S, const Epi& E) {
;     ...
;             PG8_LDB(B0, 0, 0); PG8_LDB(B1, 0, 1); PG8_SCHED; PG8_LDA(At, 0, 0); PG8_STAGE(PG8_SA(1, 1), a1 + hstep, voffA);
;             PG8_WAIT_V(8); PG8_WAIT_L(0); PG8_BAR; PG8_MMA(0, 0, At, B0); PG8_MMA(0, 1, At, B1); PG8_BAR; PG8_SCHED;
;             PG8_LDA(At, 0, 1); PG8_STAGE(PG8_SB(0, 0), b2, voffB); PG8_STAGE(PG8_SB(0, 1), b2 + hstep, voffB); PG8_STAGE(PG8_SA(0, 0), a2, voffA);
.LBB0_884:
	ds_read_b128 v[130:133], v159
	ds_read_b128 v[146:149], v159 offset:1024
	ds_read_b128 v[150:153], v159 offset:2048
	ds_read_b128 v[162:165], v159 offset:3072
	ds_read_b128 v[166:169], v160
	ds_read_b128 v[170:173], v160 offset:1024
	ds_read_b128 v[174:177], v160 offset:2048
	ds_read_b128 v[178:181], v160 offset:3072
	s_add_u32 s46, s44, 0xfffc0080
	s_addc_u32 s47, s45, -1
	s_cmp_eq_u32 s60, 12
	s_cselect_b32 s49, s35, s47
	s_cselect_b32 s48, s34, s46
	s_cselect_b32 s47, s17, s59
	s_cselect_b32 s46, s19, s58
	v_lshl_add_u64 v[214:215], s[44:45], 0, v[142:143]
	s_add_i32 m0, s50, 0xc000
	ds_read_b128 v[182:185], v161
	ds_read_b128 v[186:189], v161 offset:1024
	ds_read_b128 v[190:193], v161 offset:2048
	ds_read_b128 v[194:197], v161 offset:3072
	ds_read_b128 v[198:201], v161 offset:4096
	ds_read_b128 v[202:205], v161 offset:5120
	ds_read_b128 v[206:209], v161 offset:6144
	ds_read_b128 v[210:213], v161 offset:7168
	global_load_lds_dwordx4 v[214:215], off
	v_lshl_add_u64 v[214:215], s[44:45], 0, v[144:145]
	s_add_i32 m0, s50, 0xe000
	s_nop 0
	global_load_lds_dwordx4 v[214:215], off
	s_waitcnt vmcnt(8)
	s_waitcnt lgkmcnt(0)
	s_barrier
	s_setprio 1
	s_waitcnt lgkmcnt(0)
	v_mfma_f32_16x16x32_bf16 v[126:129], v[130:133], v[182:185], v[126:129]
	v_mfma_f32_16x16x32_bf16 v[122:125], v[150:153], v[182:185], v[122:125]
	v_mfma_f32_16x16x32_bf16 v[110:113], v[130:133], v[190:193], v[110:113]
	v_mfma_f32_16x16x32_bf16 v[106:109], v[150:153], v[190:193], v[106:109]
	v_mfma_f32_16x16x32_bf16 v[94:97], v[130:133], v[198:201], v[94:97]
	v_mfma_f32_16x16x32_bf16 v[90:93], v[150:153], v[198:201], v[90:93]
	v_mfma_f32_16x16x32_bf16 v[78:81], v[130:133], v[206:209], v[78:81]
	v_mfma_f32_16x16x32_bf16 v[74:77], v[150:153], v[206:209], v[74:77]
	v_mfma_f32_16x16x32_bf16 v[126:129], v[146:149], v[186:189], v[126:129]
	v_mfma_f32_16x16x32_bf16 v[122:125], v[162:165], v[186:189], v[122:125]
	v_mfma_f32_16x16x32_bf16 v[110:113], v[146:149], v[194:197], v[110:113]
	v_mfma_f32_16x16x32_bf16 v[106:109], v[162:165], v[194:197], v[106:109]
	v_mfma_f32_16x16x32_bf16 v[94:97], v[146:149], v[202:205], v[94:97]
	v_mfma_f32_16x16x32_bf16 v[90:93], v[162:165], v[202:205], v[90:93]
	v_mfma_f32_16x16x32_bf16 v[78:81], v[146:149], v[210:213], v[78:81]
	v_mfma_f32_16x16x32_bf16 v[74:77], v[162:165], v[210:213], v[74:77]
	s_setprio 0
	s_setprio 1
	v_mfma_f32_16x16x32_bf16 v[118:121], v[166:169], v[182:185], v[118:121]
	v_mfma_f32_16x16x32_bf16 v[114:117], v[174:177], v[182:185], v[114:117]
	v_mfma_f32_16x16x32_bf16 v[102:105], v[166:169], v[190:193], v[102:105]
	v_mfma_f32_16x16x32_bf16 v[98:101], v[174:177], v[190:193], v[98:101]
	v_mfma_f32_16x16x32_bf16 v[86:89], v[166:169], v[198:201], v[86:89]
	v_mfma_f32_16x16x32_bf16 v[82:85], v[174:177], v[198:201], v[82:85]
	v_mfma_f32_16x16x32_bf16 v[70:73], v[166:169], v[206:209], v[70:73]
	v_mfma_f32_16x16x32_bf16 v[66:69], v[174:177], v[206:209], v[66:69]
	v_mfma_f32_16x16x32_bf16 v[118:121], v[170:173], v[186:189], v[118:121]
	v_mfma_f32_16x16x32_bf16 v[114:117], v[178:181], v[186:189], v[114:117]
	v_mfma_f32_16x16x32_bf16 v[102:105], v[170:173], v[194:197], v[102:105]
	v_mfma_f32_16x16x32_bf16 v[98:101], v[178:181], v[194:197], v[98:101]
	v_mfma_f32_16x16x32_bf16 v[86:89], v[170:173], v[202:205], v[86:89]
	s_setprio 2
	s_barrier
	v_mfma_f32_16x16x32_bf16 v[82:85], v[178:181], v[202:205], v[82:85]
	v_mfma_f32_16x16x32_bf16 v[70:73], v[170:173], v[210:213], v[70:73]
	v_mfma_f32_16x16x32_bf16 v[66:69], v[178:181], v[210:213], v[66:69]
	s_setprio 0
	s_add_i32 s61, s56, s33
	v_lshl_add_u64 v[214:215], s[46:47], 0, v[138:139]
	s_mov_b32 m0, s61
	ds_read_b128 v[182:185], v161 offset:16384
	ds_read_b128 v[186:189], v161 offset:17408
	ds_read_b128 v[190:193], v161 offset:18432
	ds_read_b128 v[194:197], v161 offset:19456
	ds_read_b128 v[198:201], v161 offset:20480
	ds_read_b128 v[202:205], v161 offset:21504
	ds_read_b128 v[206:209], v161 offset:22528
	ds_read_b128 v[210:213], v161 offset:23552
	global_load_lds_dwordx4 v[214:215], off
	s_add_i32 m0, s61, 0x2000
	s_add_u32 s62, s46, 0x40000
	v_lshl_add_u64 v[216:217], s[46:47], 0, v[134:135]
	s_addc_u32 s63, s47, 0
	s_add_i32 s61, s57, s33
	global_load_lds_dwordx4 v[216:217], off
	v_lshl_add_u64 v[218:219], s[62:63], 0, v[138:139]
	s_mov_b32 m0, s61
	v_lshl_add_u64 v[220:221], s[48:49], 0, v[136:137]
	global_load_lds_dwordx4 v[218:219], off
	v_lshl_add_u64 v[218:219], s[62:63], 0, v[134:135]
	s_add_i32 m0, s61, 0x2000
	s_nop 0
	global_load_lds_dwordx4 v[218:219], off
	v_lshl_add_u64 v[218:219], s[48:49], 0, v[140:141]
	s_mov_b32 m0, s50
	s_nop 0
	global_load_lds_dwordx4 v[218:219], off
	s_mov_b32 m0, s51
	s_nop 0
	global_load_lds_dwordx4 v[220:221], off
	s_waitcnt vmcnt(8)
	s_waitcnt lgkmcnt(0)
	s_barrier
; #define PG8_STAGE(bufoff, gbase, voff) do { _Pragma("unroll") for (int _i = 0; _i < 2; ++_i) \
;         __builtin_amdgcn_global_load_lds((const unsigned*)((const char*)(gbase) + (voff)[_i]), (PG8_LAS unsigned*)(lds + (bufoff) + ldsw + _i * 8192), 16, 0, 0); } while (0)
; #define PG8_LDA(dst, b, h) do { _Pragma("unroll") for (int m = 0; m < 4; ++m) _Pragma("unroll") for (int k = 0; k < 2; ++k) dst[m][k] = *(const PG8_LAS bf16x8*)(lds + PG8_SA(b, h) + aoff + m * 2048 + k * 1024); } while (0)
; #define PG8_LDB(dst, b, h) do { _Pragma("unroll") for (int n = 0; n < 2; ++n) _Pragma("unroll") for (int k = 0; k < 2; ++k) dst[n][k] = *(const PG8_LAS bf16x8*)(lds + PG8_SB(b, h) + boff + n * 2048 + k * 1024); } while (0)
; #define PG8_MMA(ai, bj, At, Bt) do { __builtin_amdgcn_s_setprio(1); _Pragma("unroll") for (int m = 0; m < 4; ++m) _Pragma("unroll") for (int n = 0; n < 2; ++n) _Pragma("unroll") for (int k = 0; k < 2; ++k) \
;         acc[ai][bj][m][n] = __builtin_amdgcn_mfma_f32_16x16x32_bf16(Bt[n][k], At[m][k], acc[ai][bj][m][n], 0, 0, 0); __builtin_amdgcn_s_setprio(0); } while (0)
; #define PG8_WAIT_V(n) asm volatile("s_waitcnt vmcnt(" #n ")" ::: "memory")
; #define PG8_WAIT_L(n) asm volatile("s_waitcnt lgkmcnt(" #n ")" ::: "memory")
; #define PG8_BAR __builtin_amdgcn_s_barrier()
; #define PG8_SCHED __builtin_amdgcn_sched_barrier(0)
; template <class Epi, class Sched, bool ALIGN_EPI = false, bool SP2 = false>
; __device__ __forceinline__ void gemm_phase(PG8_LAS unsigned char* lds, const Gemm g, const Sched& S, const Epi& E) {
;     ...
;             PG8_WAIT_V(8); PG8_WAIT_L(0); PG8_BAR; PG8_MMA(1, 0, At, B0); PG8_MMA(1, 1, At, B1); PG8_BAR; PG8_SCHED;
;             PG8_LDB(B0, 1, 0); PG8_LDB(B1, 1, 1); PG8_SCHED; PG8_LDA(At, 1, 0); PG8_STAGE(PG8_SA(0, 1), a2 + hstep, voffA);
;             PG8_WAIT_V(8); PG8_WAIT_L(0); PG8_BAR; PG8_MMA(0, 0, At, B0); PG8_MMA(0, 1, At, B1); PG8_BAR; PG8_SCHED;
	s_setprio 1
	s_waitcnt lgkmcnt(0)
	v_mfma_f32_16x16x32_bf16 v[62:65], v[130:133], v[182:185], v[62:65]
	v_mfma_f32_16x16x32_bf16 v[58:61], v[150:153], v[182:185], v[58:61]
	v_mfma_f32_16x16x32_bf16 v[46:49], v[130:133], v[190:193], v[46:49]
	v_mfma_f32_16x16x32_bf16 v[42:45], v[150:153], v[190:193], v[42:45]
	v_mfma_f32_16x16x32_bf16 v[30:33], v[130:133], v[198:201], v[30:33]
	v_mfma_f32_16x16x32_bf16 v[26:29], v[150:153], v[198:201], v[26:29]
	v_mfma_f32_16x16x32_bf16 v[14:17], v[130:133], v[206:209], v[14:17]
	v_mfma_f32_16x16x32_bf16 v[10:13], v[150:153], v[206:209], v[10:13]
	v_mfma_f32_16x16x32_bf16 v[62:65], v[146:149], v[186:189], v[62:65]
	v_mfma_f32_16x16x32_bf16 v[58:61], v[162:165], v[186:189], v[58:61]
	v_mfma_f32_16x16x32_bf16 v[46:49], v[146:149], v[194:197], v[46:49]
	v_mfma_f32_16x16x32_bf16 v[42:45], v[162:165], v[194:197], v[42:45]
	v_mfma_f32_16x16x32_bf16 v[30:33], v[146:149], v[202:205], v[30:33]
	v_mfma_f32_16x16x32_bf16 v[26:29], v[162:165], v[202:205], v[26:29]
	v_mfma_f32_16x16x32_bf16 v[14:17], v[146:149], v[210:213], v[14:17]
	v_mfma_f32_16x16x32_bf16 v[10:13], v[162:165], v[210:213], v[10:13]
	s_setprio 0
	s_setprio 1
	v_mfma_f32_16x16x32_bf16 v[54:57], v[166:169], v[182:185], v[54:57]
	v_mfma_f32_16x16x32_bf16 v[50:53], v[174:177], v[182:185], v[50:53]
	v_mfma_f32_16x16x32_bf16 v[38:41], v[166:169], v[190:193], v[38:41]
	v_mfma_f32_16x16x32_bf16 v[34:37], v[174:177], v[190:193], v[34:37]
	v_mfma_f32_16x16x32_bf16 v[22:25], v[166:169], v[198:201], v[22:25]
	v_mfma_f32_16x16x32_bf16 v[18:21], v[174:177], v[198:201], v[18:21]
	v_mfma_f32_16x16x32_bf16 v[6:9], v[166:169], v[206:209], v[6:9]
	v_mfma_f32_16x16x32_bf16 v[2:5], v[174:177], v[206:209], v[2:5]
	v_mfma_f32_16x16x32_bf16 v[54:57], v[170:173], v[186:189], v[54:57]
	v_mfma_f32_16x16x32_bf16 v[50:53], v[178:181], v[186:189], v[50:53]
	v_mfma_f32_16x16x32_bf16 v[38:41], v[170:173], v[194:197], v[38:41]
	v_mfma_f32_16x16x32_bf16 v[34:37], v[178:181], v[194:197], v[34:37]
	v_mfma_f32_16x16x32_bf16 v[22:25], v[170:173], v[202:205], v[22:25]
	s_setprio 2
	s_barrier
	v_mfma_f32_16x16x32_bf16 v[18:21], v[178:181], v[202:205], v[18:21]
	v_mfma_f32_16x16x32_bf16 v[6:9], v[170:173], v[210:213], v[6:9]
	v_mfma_f32_16x16x32_bf16 v[2:5], v[178:181], v[210:213], v[2:5]
	s_setprio 0
	s_add_i32 s61, 0, 0x18000
	s_add_i32 s62, 0, 0x1c000
	v_add_u32_e32 v162, s61, v155
	v_add_u32_e32 v178, s62, v155
	ds_read_b128 v[130:133], v162
	ds_read_b128 v[146:149], v162 offset:1024
	ds_read_b128 v[150:153], v162 offset:2048
	ds_read_b128 v[162:165], v162 offset:3072
	ds_read_b128 v[166:169], v178
	ds_read_b128 v[170:173], v178 offset:1024
	ds_read_b128 v[174:177], v178 offset:2048
	ds_read_b128 v[178:181], v178 offset:3072
	s_add_u32 s48, s48, 0x40000
	s_addc_u32 s49, s49, 0
	s_mov_b32 m0, s52
	v_lshl_add_u64 v[222:223], s[48:49], 0, v[140:141]
	ds_read_b128 v[182:185], v161 offset:32768
	ds_read_b128 v[186:189], v161 offset:33792
	ds_read_b128 v[190:193], v161 offset:34816
	ds_read_b128 v[194:197], v161 offset:35840
	ds_read_b128 v[198:201], v161 offset:36864
	ds_read_b128 v[202:205], v161 offset:37888
	ds_read_b128 v[206:209], v161 offset:38912
	ds_read_b128 v[210:213], v161 offset:39936
	global_load_lds_dwordx4 v[222:223], off
	v_lshl_add_u64 v[222:223], s[48:49], 0, v[136:137]
	s_mov_b32 m0, s53
	s_nop 0
	global_load_lds_dwordx4 v[222:223], off
	s_waitcnt vmcnt(8)
	s_waitcnt lgkmcnt(0)
	s_barrier
	s_setprio 1
	s_waitcnt lgkmcnt(0)
	v_mfma_f32_16x16x32_bf16 v[126:129], v[130:133], v[182:185], v[126:129]
	v_mfma_f32_16x16x32_bf16 v[122:125], v[150:153], v[182:185], v[122:125]
	v_mfma_f32_16x16x32_bf16 v[110:113], v[130:133], v[190:193], v[110:113]
	v_mfma_f32_16x16x32_bf16 v[106:109], v[150:153], v[190:193], v[106:109]
	v_mfma_f32_16x16x32_bf16 v[94:97], v[130:133], v[198:201], v[94:97]
	v_mfma_f32_16x16x32_bf16 v[90:93], v[150:153], v[198:201], v[90:93]
	v_mfma_f32_16x16x32_bf16 v[78:81], v[130:133], v[206:209], v[78:81]
	v_mfma_f32_16x16x32_bf16 v[74:77], v[150:153], v[206:209], v[74:77]
	v_mfma_f32_16x16x32_bf16 v[126:129], v[146:149], v[186:189], v[126:129]
	v_mfma_f32_16x16x32_bf16 v[122:125], v[162:165], v[186:189], v[122:125]
	v_mfma_f32_16x16x32_bf16 v[110:113], v[146:149], v[194:197], v[110:113]
	v_mfma_f32_16x16x32_bf16 v[106:109], v[162:165], v[194:197], v[106:109]
	v_mfma_f32_16x16x32_bf16 v[94:97], v[146:149], v[202:205], v[94:97]
	v_mfma_f32_16x16x32_bf16 v[90:93], v[162:165], v[202:205], v[90:93]
	v_mfma_f32_16x16x32_bf16 v[78:81], v[146:149], v[210:213], v[78:81]
	v_mfma_f32_16x16x32_bf16 v[74:77], v[162:165], v[210:213], v[74:77]
	s_setprio 0
	s_setprio 1
	v_mfma_f32_16x16x32_bf16 v[118:121], v[166:169], v[182:185], v[118:121]
	v_mfma_f32_16x16x32_bf16 v[114:117], v[174:177], v[182:185], v[114:117]
	v_mfma_f32_16x16x32_bf16 v[102:105], v[166:169], v[190:193], v[102:105]
	v_mfma_f32_16x16x32_bf16 v[98:101], v[174:177], v[190:193], v[98:101]
	v_mfma_f32_16x16x32_bf16 v[86:89], v[166:169], v[198:201], v[86:89]
	v_mfma_f32_16x16x32_bf16 v[82:85], v[174:177], v[198:201], v[82:85]
	v_mfma_f32_16x16x32_bf16 v[70:73], v[166:169], v[206:209], v[70:73]
	v_mfma_f32_16x16x32_bf16 v[66:69], v[174:177], v[206:209], v[66:69]
	v_mfma_f32_16x16x32_bf16 v[118:121], v[170:173], v[186:189], v[118:121]
	v_mfma_f32_16x16x32_bf16 v[114:117], v[178:181], v[186:189], v[114:117]
	v_mfma_f32_16x16x32_bf16 v[102:105], v[170:173], v[194:197], v[102:105]
	v_mfma_f32_16x16x32_bf16 v[98:101], v[178:181], v[194:197], v[98:101]
	v_mfma_f32_16x16x32_bf16 v[86:89], v[170:173], v[202:205], v[86:89]
	s_setprio 2
	s_barrier
; #define PG8_STAGE(bufoff, gbase, voff) do { _Pragma("unroll") for (int _i = 0; _i < 2; ++_i) \
;         __builtin_amdgcn_global_load_lds((const unsigned*)((const char*)(gbase) + (voff)[_i]), (PG8_LAS unsigned*)(lds + (bufoff) + ldsw + _i * 8192), 16, 0, 0); } while (0)
; #define PG8_LDA(dst, b, h) do { _Pragma("unroll") for (int m = 0; m < 4; ++m) _Pragma("unroll") for (int k = 0; k < 2; ++k) dst[m][k] = *(const PG8_LAS bf16x8*)(lds + PG8_SA(b, h) + aoff + m * 2048 + k * 1024); } while (0)
; #define PG8_MMA(ai, bj, At, Bt) do { __builtin_amdgcn_s_setprio(1); _Pragma("unroll") for (int m = 0; m < 4; ++m) _Pragma("unroll") for (int n = 0; n < 2; ++n) _Pragma("unroll") for (int k = 0; k < 2; ++k) \
;         acc[ai][bj][m][n] = __builtin_amdgcn_mfma_f32_16x16x32_bf16(Bt[n][k], At[m][k], acc[ai][bj][m][n], 0, 0, 0); __builtin_amdgcn_s_setprio(0); } while (0)
; #define PG8_WAIT_V(n) asm volatile("s_waitcnt vmcnt(" #n ")" ::: "memory")
; #define PG8_WAIT_L(n) asm volatile("s_waitcnt lgkmcnt(" #n ")" ::: "memory")
; #define PG8_BAR __builtin_amdgcn_s_barrier()
; #define PG8_SCHED __builtin_amdgcn_sched_barrier(0)
; template <class Epi, class Sched, bool ALIGN_EPI = false, bool SP2 = false>
; __device__ __forceinline__ void gemm_phase(PG8_LAS unsigned char* lds, const Gemm g, const Sched& S, const Epi& E) {
;     ...
;             PG8_WAIT_V(8); PG8_WAIT_L(0); PG8_BAR; PG8_MMA(0, 0, At, B0); PG8_MMA(0, 1, At, B1); PG8_BAR; PG8_SCHED;
;             PG8_LDA(At, 1, 1); PG8_STAGE(PG8_SB(1, 0), b3, voffB); PG8_STAGE(PG8_SB(1, 1), b3 + hstep, voffB); PG8_STAGE(PG8_SA(1, 0), a3, voffA);
;             PG8_WAIT_V(8); PG8_WAIT_L(0); PG8_BAR; PG8_MMA(1, 0, At, B0); PG8_MMA(1, 1, At, B1); PG8_BAR; PG8_SCHED;
	v_mfma_f32_16x16x32_bf16 v[82:85], v[178:181], v[202:205], v[82:85]
	v_mfma_f32_16x16x32_bf16 v[70:73], v[170:173], v[210:213], v[70:73]
	v_mfma_f32_16x16x32_bf16 v[66:69], v[178:181], v[210:213], v[66:69]
	s_setprio 0
	s_add_i32 s48, s61, s33
	v_lshl_add_u64 v[214:215], v[214:215], 0, s[12:13]
	s_mov_b32 m0, s48
	ds_read_b128 v[182:185], v161 offset:49152
	ds_read_b128 v[186:189], v161 offset:50176
	ds_read_b128 v[190:193], v161 offset:51200
	ds_read_b128 v[194:197], v161 offset:52224
	ds_read_b128 v[198:201], v161 offset:53248
	ds_read_b128 v[202:205], v161 offset:54272
	ds_read_b128 v[206:209], v161 offset:55296
	ds_read_b128 v[210:213], v161 offset:56320
	global_load_lds_dwordx4 v[214:215], off
	s_add_i32 m0, s48, 0x2000
	s_add_u32 s46, s46, 0x40080
	v_lshl_add_u64 v[214:215], v[216:217], 0, s[12:13]
	s_addc_u32 s47, s47, 0
	s_add_i32 s48, s62, s33
	global_load_lds_dwordx4 v[214:215], off
	v_lshl_add_u64 v[214:215], s[46:47], 0, v[138:139]
	s_mov_b32 m0, s48
	s_nop 0
	global_load_lds_dwordx4 v[214:215], off
	v_lshl_add_u64 v[214:215], s[46:47], 0, v[134:135]
	s_add_i32 m0, s48, 0x2000
	s_nop 0
	global_load_lds_dwordx4 v[214:215], off
	v_lshl_add_u64 v[214:215], v[218:219], 0, s[12:13]
	s_mov_b32 m0, s54
	s_nop 0
	global_load_lds_dwordx4 v[214:215], off
	v_lshl_add_u64 v[214:215], v[220:221], 0, s[12:13]
	s_mov_b32 m0, s55
	s_nop 0
	global_load_lds_dwordx4 v[214:215], off
	s_waitcnt vmcnt(8)
	s_waitcnt lgkmcnt(0)
	s_barrier
	s_setprio 1
	s_waitcnt lgkmcnt(0)
	v_mfma_f32_16x16x32_bf16 v[62:65], v[130:133], v[182:185], v[62:65]
	v_mfma_f32_16x16x32_bf16 v[58:61], v[150:153], v[182:185], v[58:61]
	v_mfma_f32_16x16x32_bf16 v[46:49], v[130:133], v[190:193], v[46:49]
	v_mfma_f32_16x16x32_bf16 v[42:45], v[150:153], v[190:193], v[42:45]
	v_mfma_f32_16x16x32_bf16 v[30:33], v[130:133], v[198:201], v[30:33]
	v_mfma_f32_16x16x32_bf16 v[26:29], v[150:153], v[198:201], v[26:29]
	v_mfma_f32_16x16x32_bf16 v[14:17], v[130:133], v[206:209], v[14:17]
	v_mfma_f32_16x16x32_bf16 v[10:13], v[150:153], v[206:209], v[10:13]
	v_mfma_f32_16x16x32_bf16 v[62:65], v[146:149], v[186:189], v[62:65]
	v_mfma_f32_16x16x32_bf16 v[58:61], v[162:165], v[186:189], v[58:61]
	v_mfma_f32_16x16x32_bf16 v[46:49], v[146:149], v[194:197], v[46:49]
	v_mfma_f32_16x16x32_bf16 v[42:45], v[162:165], v[194:197], v[42:45]
	v_mfma_f32_16x16x32_bf16 v[30:33], v[146:149], v[202:205], v[30:33]
	v_mfma_f32_16x16x32_bf16 v[26:29], v[162:165], v[202:205], v[26:29]
	v_mfma_f32_16x16x32_bf16 v[14:17], v[146:149], v[210:213], v[14:17]
	v_mfma_f32_16x16x32_bf16 v[10:13], v[162:165], v[210:213], v[10:13]
	s_setprio 0
	s_setprio 1
	v_mfma_f32_16x16x32_bf16 v[54:57], v[166:169], v[182:185], v[54:57]
	v_mfma_f32_16x16x32_bf16 v[50:53], v[174:177], v[182:185], v[50:53]
	v_mfma_f32_16x16x32_bf16 v[38:41], v[166:169], v[190:193], v[38:41]
	v_mfma_f32_16x16x32_bf16 v[34:37], v[174:177], v[190:193], v[34:37]
	v_mfma_f32_16x16x32_bf16 v[22:25], v[166:169], v[198:201], v[22:25]
	v_mfma_f32_16x16x32_bf16 v[18:21], v[174:177], v[198:201], v[18:21]
	v_mfma_f32_16x16x32_bf16 v[6:9], v[166:169], v[206:209], v[6:9]
	v_mfma_f32_16x16x32_bf16 v[2:5], v[174:177], v[206:209], v[2:5]
	v_mfma_f32_16x16x32_bf16 v[54:57], v[170:173], v[186:189], v[54:57]
	v_mfma_f32_16x16x32_bf16 v[50:53], v[178:181], v[186:189], v[50:53]
	v_mfma_f32_16x16x32_bf16 v[38:41], v[170:173], v[194:197], v[38:41]
	v_mfma_f32_16x16x32_bf16 v[34:37], v[178:181], v[194:197], v[34:37]
	v_mfma_f32_16x16x32_bf16 v[22:25], v[170:173], v[202:205], v[22:25]
	s_setprio 2
	s_barrier
	v_mfma_f32_16x16x32_bf16 v[18:21], v[178:181], v[202:205], v[18:21]
	v_mfma_f32_16x16x32_bf16 v[6:9], v[170:173], v[210:213], v[6:9]
	v_mfma_f32_16x16x32_bf16 v[2:5], v[178:181], v[210:213], v[2:5]
	s_setprio 0
	s_add_i32 s60, s60, 2
	s_add_u32 s44, s44, 0x100
	s_addc_u32 s45, s45, 0
	s_add_u32 s58, s58, 0x100
	s_addc_u32 s59, s59, 0
	s_cmp_gt_u32 s60, 13
	s_cbranch_scc0 .LBB0_884
	s_and_b64 vcc, exec, s[14:15]
	s_cbranch_vccz .LBB0_887
	s_barrier

; #define PG8_STAGE(bufoff, gbase, voff) do { _Pragma("unroll") for (int _i = 0; _i < 2; ++_i) \
;         __builtin_amdgcn_global_load_lds((const unsigned*)((const char*)(gbase) + (voff)[_i]), (PG8_LAS unsigned*)(lds + (bufoff) + ldsw + _i * 8192), 16, 0, 0); } while (0)
; #define PG8_LDA(dst, b, h) do { _Pragma("unroll") for (int m = 0; m < 4; ++m) _Pragma("unroll") for (int k = 0; k < 2; ++k) dst[m][k] = *(const PG8_LAS bf16x8*)(lds + PG8_SA(b, h) + aoff + m * 2048 + k * 1024); } while (0)
; #define PG8_LDB(dst, b, h) do { _Pragma("unroll") for (int n = 0; n < 2; ++n) _Pragma("unroll") for (int k = 0; k < 2; ++k) dst[n][k] = *(const PG8_LAS bf16x8*)(lds + PG8_SB(b, h) + boff + n * 2048 + k * 1024); } while (0)
; #define PG8_MMA(ai, bj, At, Bt) do { __builtin_amdgcn_s_setprio(1); _Pragma("unroll") for (int m = 0; m < 4; ++m) _Pragma("unroll") for (int n = 0; n < 2; ++n) _Pragma("unroll") for (int k = 0; k < 2; ++k) \
;         acc[ai][bj][m][n] = __builtin_amdgcn_mfma_f32_16x16x32_bf16(Bt[n][k], At[m][k], acc[ai][bj][m][n], 0, 0, 0); __builtin_amdgcn_s_setprio(0); } while (0)
; #define PG8_WAIT_V(n) asm volatile("s_waitcnt vmcnt(" #n ")" ::: "memory")
; #define PG8_WAIT_L(n) asm volatile("s_waitcnt lgkmcnt(" #n ")" ::: "memory")
; #define PG8_BAR __builtin_amdgcn_s_barrier()
; #define PG8_SCHED __builtin_amdgcn_sched_barrier(0)
; template <class Epi, class Sched, bool ALIGN_EPI = false, bool SP2 = false>
; __device__ __forceinline__ void gemm_phase(PG8_LAS unsigned char* lds, const Gemm g, const Sched& S, const Epi& E) {
;     ...
;             const bool last = (t == nt - 2);
;             const char* a1 = cA + (size_t)(t + 1) * kstep;
;             const char* a2 = last ? nA : cA + (size_t)(t + 2) * kstep; const char* b2 = last ? nB : cB + (size_t)(t + 2) * kstep;
;             const char* a3 = a2 + kstep; const char* b3 = b2 + kstep;
;             if (last && has_next) S.a_ready(nxt);
;             if constexpr (SP2) {
;             PG8_LDB(B0, 0, 0); PG8_LDB(B1, 0, 1); PG8_SCHED; PG8_LDA(At, 0, 0); PG8_STAGE(PG8_SA(1, 1), a1 + hstep, voffA);
;             PG8_WAIT_V(8); PG8_WAIT_L(0); PG8_BAR; PG8_MMA(0, 0, At, B0); PG8_MMA(0, 1, At, B1); PG8_BAR; PG8_SCHED;
;             PG8_LDA(At, 0, 1); PG8_STAGE(PG8_SB(0, 0), b2, voffB); PG8_STAGE(PG8_SB(0, 1), b2 + hstep, voffB); PG8_STAGE(PG8_SA(0, 0), a2, voffA);
.LBB0_968:
	v_add_u32_e32 v162, s45, v148
	v_add_u32_e32 v178, s46, v148
	s_add_u32 s22, s8, s20
	ds_read_b128 v[150:153], v162
	ds_read_b128 v[154:157], v162 offset:1024
	ds_read_b128 v[158:161], v162 offset:2048
	ds_read_b128 v[162:165], v162 offset:3072
	ds_read_b128 v[166:169], v178
	ds_read_b128 v[170:173], v178 offset:1024
	ds_read_b128 v[174:177], v178 offset:2048
	ds_read_b128 v[178:181], v178 offset:3072
	s_addc_u32 s23, s9, s21
	s_add_u32 s22, s22, 0x100
	s_addc_u32 s23, s23, 0
	s_add_u32 s51, s48, s20
	s_addc_u32 s52, s49, s21
	s_cmpk_eq_i32 s20, 0x700
	s_cselect_b32 s25, s19, s23
	s_cselect_b32 s24, s18, s22
	s_cselect_b32 s23, s13, s52
	s_cselect_b32 s22, s15, s51
	v_lshl_add_u64 v[214:215], v[142:143], 0, s[20:21]
	s_add_i32 m0, s5, 0xc000
	ds_read_b128 v[182:185], v149
	ds_read_b128 v[186:189], v149 offset:1024
	ds_read_b128 v[190:193], v149 offset:2048
	ds_read_b128 v[194:197], v149 offset:3072
	ds_read_b128 v[198:201], v149 offset:4096
	ds_read_b128 v[202:205], v149 offset:5120
	ds_read_b128 v[206:209], v149 offset:6144
	ds_read_b128 v[210:213], v149 offset:7168
	global_load_lds_dwordx4 v[214:215], off
	v_lshl_add_u64 v[214:215], v[144:145], 0, s[20:21]
	s_add_i32 m0, s5, 0xe000
	s_nop 0
	global_load_lds_dwordx4 v[214:215], off
	s_waitcnt vmcnt(8)
	s_waitcnt lgkmcnt(0)
	s_barrier
	s_setprio 1
	s_waitcnt lgkmcnt(0)
	v_mfma_f32_16x16x32_bf16 v[126:129], v[150:153], v[182:185], v[126:129]
	v_mfma_f32_16x16x32_bf16 v[122:125], v[158:161], v[182:185], v[122:125]
	v_mfma_f32_16x16x32_bf16 v[114:117], v[150:153], v[190:193], v[114:117]
	v_mfma_f32_16x16x32_bf16 v[106:109], v[158:161], v[190:193], v[106:109]
	v_mfma_f32_16x16x32_bf16 v[98:101], v[150:153], v[198:201], v[98:101]
	v_mfma_f32_16x16x32_bf16 v[90:93], v[158:161], v[198:201], v[90:93]
	v_mfma_f32_16x16x32_bf16 v[82:85], v[150:153], v[206:209], v[82:85]
	v_mfma_f32_16x16x32_bf16 v[74:77], v[158:161], v[206:209], v[74:77]
	v_mfma_f32_16x16x32_bf16 v[126:129], v[154:157], v[186:189], v[126:129]
	v_mfma_f32_16x16x32_bf16 v[122:125], v[162:165], v[186:189], v[122:125]
	v_mfma_f32_16x16x32_bf16 v[114:117], v[154:157], v[194:197], v[114:117]
	v_mfma_f32_16x16x32_bf16 v[106:109], v[162:165], v[194:197], v[106:109]
	v_mfma_f32_16x16x32_bf16 v[98:101], v[154:157], v[202:205], v[98:101]
	v_mfma_f32_16x16x32_bf16 v[90:93], v[162:165], v[202:205], v[90:93]
	v_mfma_f32_16x16x32_bf16 v[82:85], v[154:157], v[210:213], v[82:85]
	v_mfma_f32_16x16x32_bf16 v[74:77], v[162:165], v[210:213], v[74:77]
	s_setprio 0
	s_setprio 1
	v_mfma_f32_16x16x32_bf16 v[118:121], v[166:169], v[182:185], v[118:121]
	v_mfma_f32_16x16x32_bf16 v[110:113], v[174:177], v[182:185], v[110:113]
	v_mfma_f32_16x16x32_bf16 v[102:105], v[166:169], v[190:193], v[102:105]
	v_mfma_f32_16x16x32_bf16 v[94:97], v[174:177], v[190:193], v[94:97]
	v_mfma_f32_16x16x32_bf16 v[86:89], v[166:169], v[198:201], v[86:89]
	v_mfma_f32_16x16x32_bf16 v[78:81], v[174:177], v[198:201], v[78:81]
	v_mfma_f32_16x16x32_bf16 v[70:73], v[166:169], v[206:209], v[70:73]
	v_mfma_f32_16x16x32_bf16 v[66:69], v[174:177], v[206:209], v[66:69]
	v_mfma_f32_16x16x32_bf16 v[118:121], v[170:173], v[186:189], v[118:121]
	v_mfma_f32_16x16x32_bf16 v[110:113], v[178:181], v[186:189], v[110:113]
	v_mfma_f32_16x16x32_bf16 v[102:105], v[170:173], v[194:197], v[102:105]
	v_mfma_f32_16x16x32_bf16 v[94:97], v[178:181], v[194:197], v[94:97]
	v_mfma_f32_16x16x32_bf16 v[86:89], v[170:173], v[202:205], v[86:89]
	s_setprio 2
	s_barrier
	v_mfma_f32_16x16x32_bf16 v[78:81], v[178:181], v[202:205], v[78:81]
	v_mfma_f32_16x16x32_bf16 v[70:73], v[170:173], v[210:213], v[70:73]
	v_mfma_f32_16x16x32_bf16 v[66:69], v[178:181], v[210:213], v[66:69]
	s_setprio 0
	s_add_i32 s51, s45, s38
	v_lshl_add_u64 v[214:215], s[22:23], 0, v[130:131]
	s_mov_b32 m0, s51
	ds_read_b128 v[182:185], v149 offset:16384
	ds_read_b128 v[186:189], v149 offset:17408
	ds_read_b128 v[190:193], v149 offset:18432
	ds_read_b128 v[194:197], v149 offset:19456
	ds_read_b128 v[198:201], v149 offset:20480
	ds_read_b128 v[202:205], v149 offset:21504
	ds_read_b128 v[206:209], v149 offset:22528
	ds_read_b128 v[210:213], v149 offset:23552
	global_load_lds_dwordx4 v[214:215], off
	s_add_i32 m0, s51, 0x2000
	s_add_u32 s52, s22, 0x40000
	v_lshl_add_u64 v[216:217], s[22:23], 0, v[132:133]
	s_addc_u32 s53, s23, 0
	s_add_i32 s51, s46, s38
	global_load_lds_dwordx4 v[216:217], off
	v_lshl_add_u64 v[218:219], s[52:53], 0, v[130:131]
	s_mov_b32 m0, s51
	v_lshl_add_u64 v[220:221], s[24:25], 0, v[132:133]
	global_load_lds_dwordx4 v[218:219], off
	v_lshl_add_u64 v[218:219], s[52:53], 0, v[132:133]
	s_add_i32 m0, s51, 0x2000
	s_nop 0
	global_load_lds_dwordx4 v[218:219], off
	v_lshl_add_u64 v[218:219], s[24:25], 0, v[130:131]
	s_mov_b32 m0, s5
	s_nop 0
	global_load_lds_dwordx4 v[218:219], off
	s_mov_b32 m0, s39
	s_nop 0
	global_load_lds_dwordx4 v[220:221], off
	s_waitcnt vmcnt(8)
	s_waitcnt lgkmcnt(0)
	s_barrier
; #define PG8_STAGE(bufoff, gbase, voff) do { _Pragma("unroll") for (int _i = 0; _i < 2; ++_i) \
;         __builtin_amdgcn_global_load_lds((const unsigned*)((const char*)(gbase) + (voff)[_i]), (PG8_LAS unsigned*)(lds + (bufoff) + ldsw + _i * 8192), 16, 0, 0); } while (0)
; #define PG8_LDA(dst, b, h) do { _Pragma("unroll") for (int m = 0; m < 4; ++m) _Pragma("unroll") for (int k = 0; k < 2; ++k) dst[m][k] = *(const PG8_LAS bf16x8*)(lds + PG8_SA(b, h) + aoff + m * 2048 + k * 1024); } while (0)
; #define PG8_LDB(dst, b, h) do { _Pragma("unroll") for (int n = 0; n < 2; ++n) _Pragma("unroll") for (int k = 0; k < 2; ++k) dst[n][k] = *(const PG8_LAS bf16x8*)(lds + PG8_SB(b, h) + boff + n * 2048 + k * 1024); } while (0)
; #define PG8_MMA(ai, bj, At, Bt) do { __builtin_amdgcn_s_setprio(1); _Pragma("unroll") for (int m = 0; m < 4; ++m) _Pragma("unroll") for (int n = 0; n < 2; ++n) _Pragma("unroll") for (int k = 0; k < 2; ++k) \
;         acc[ai][bj][m][n] = __builtin_amdgcn_mfma_f32_16x16x32_bf16(Bt[n][k], At[m][k], acc[ai][bj][m][n], 0, 0, 0); __builtin_amdgcn_s_setprio(0); } while (0)
; #define PG8_WAIT_V(n) asm volatile("s_waitcnt vmcnt(" #n ")" ::: "memory")
; #define PG8_WAIT_L(n) asm volatile("s_waitcnt lgkmcnt(" #n ")" ::: "memory")
; #define PG8_BAR __builtin_amdgcn_s_barrier()
; #define PG8_SCHED __builtin_amdgcn_sched_barrier(0)
; template <class Epi, class Sched, bool ALIGN_EPI = false, bool SP2 = false>
; __device__ __forceinline__ void gemm_phase(PG8_LAS unsigned char* lds, const Gemm g, const Sched& S, const Epi& E) {
;     ...
;             PG8_WAIT_V(8); PG8_WAIT_L(0); PG8_BAR; PG8_MMA(1, 0, At, B0); PG8_MMA(1, 1, At, B1); PG8_BAR; PG8_SCHED;
;             PG8_LDB(B0, 1, 0); PG8_LDB(B1, 1, 1); PG8_SCHED; PG8_LDA(At, 1, 0); PG8_STAGE(PG8_SA(0, 1), a2 + hstep, voffA);
;             PG8_WAIT_V(8); PG8_WAIT_L(0); PG8_BAR; PG8_MMA(0, 0, At, B0); PG8_MMA(0, 1, At, B1); PG8_BAR; PG8_SCHED;
	s_setprio 1
	s_waitcnt lgkmcnt(0)
	v_mfma_f32_16x16x32_bf16 v[62:65], v[150:153], v[182:185], v[62:65]
	v_mfma_f32_16x16x32_bf16 v[58:61], v[158:161], v[182:185], v[58:61]
	v_mfma_f32_16x16x32_bf16 v[50:53], v[150:153], v[190:193], v[50:53]
	v_mfma_f32_16x16x32_bf16 v[42:45], v[158:161], v[190:193], v[42:45]
	v_mfma_f32_16x16x32_bf16 v[34:37], v[150:153], v[198:201], v[34:37]
	v_mfma_f32_16x16x32_bf16 v[26:29], v[158:161], v[198:201], v[26:29]
	v_mfma_f32_16x16x32_bf16 v[18:21], v[150:153], v[206:209], v[18:21]
	v_mfma_f32_16x16x32_bf16 v[10:13], v[158:161], v[206:209], v[10:13]
	v_mfma_f32_16x16x32_bf16 v[62:65], v[154:157], v[186:189], v[62:65]
	v_mfma_f32_16x16x32_bf16 v[58:61], v[162:165], v[186:189], v[58:61]
	v_mfma_f32_16x16x32_bf16 v[50:53], v[154:157], v[194:197], v[50:53]
	v_mfma_f32_16x16x32_bf16 v[42:45], v[162:165], v[194:197], v[42:45]
	v_mfma_f32_16x16x32_bf16 v[34:37], v[154:157], v[202:205], v[34:37]
	v_mfma_f32_16x16x32_bf16 v[26:29], v[162:165], v[202:205], v[26:29]
	v_mfma_f32_16x16x32_bf16 v[18:21], v[154:157], v[210:213], v[18:21]
	v_mfma_f32_16x16x32_bf16 v[10:13], v[162:165], v[210:213], v[10:13]
	s_setprio 0
	s_setprio 1
	v_mfma_f32_16x16x32_bf16 v[54:57], v[166:169], v[182:185], v[54:57]
	v_mfma_f32_16x16x32_bf16 v[46:49], v[174:177], v[182:185], v[46:49]
	v_mfma_f32_16x16x32_bf16 v[38:41], v[166:169], v[190:193], v[38:41]
	v_mfma_f32_16x16x32_bf16 v[30:33], v[174:177], v[190:193], v[30:33]
	v_mfma_f32_16x16x32_bf16 v[22:25], v[166:169], v[198:201], v[22:25]
	v_mfma_f32_16x16x32_bf16 v[14:17], v[174:177], v[198:201], v[14:17]
	v_mfma_f32_16x16x32_bf16 v[6:9], v[166:169], v[206:209], v[6:9]
	v_mfma_f32_16x16x32_bf16 v[2:5], v[174:177], v[206:209], v[2:5]
	v_mfma_f32_16x16x32_bf16 v[54:57], v[170:173], v[186:189], v[54:57]
	v_mfma_f32_16x16x32_bf16 v[46:49], v[178:181], v[186:189], v[46:49]
	v_mfma_f32_16x16x32_bf16 v[38:41], v[170:173], v[194:197], v[38:41]
	v_mfma_f32_16x16x32_bf16 v[30:33], v[178:181], v[194:197], v[30:33]
	v_mfma_f32_16x16x32_bf16 v[22:25], v[170:173], v[202:205], v[22:25]
	s_setprio 2
	s_barrier
	v_mfma_f32_16x16x32_bf16 v[14:17], v[178:181], v[202:205], v[14:17]
	v_mfma_f32_16x16x32_bf16 v[6:9], v[170:173], v[210:213], v[6:9]
	v_mfma_f32_16x16x32_bf16 v[2:5], v[178:181], v[210:213], v[2:5]
	s_setprio 0
	s_add_i32 s51, 0, 0x18000
	s_add_i32 s52, 0, 0x1c000
	v_add_u32_e32 v162, s51, v148
	v_add_u32_e32 v178, s52, v148
	ds_read_b128 v[150:153], v162
	ds_read_b128 v[154:157], v162 offset:1024
	ds_read_b128 v[158:161], v162 offset:2048
	ds_read_b128 v[162:165], v162 offset:3072
	ds_read_b128 v[166:169], v178
	ds_read_b128 v[170:173], v178 offset:1024
	ds_read_b128 v[174:177], v178 offset:2048
	ds_read_b128 v[178:181], v178 offset:3072
	s_add_u32 s24, s24, 0x40000
	s_addc_u32 s25, s25, 0
	s_mov_b32 m0, s40
	v_lshl_add_u64 v[222:223], s[24:25], 0, v[130:131]
	ds_read_b128 v[182:185], v149 offset:32768
	ds_read_b128 v[186:189], v149 offset:33792
	ds_read_b128 v[190:193], v149 offset:34816
	ds_read_b128 v[194:197], v149 offset:35840
	ds_read_b128 v[198:201], v149 offset:36864
	ds_read_b128 v[202:205], v149 offset:37888
	ds_read_b128 v[206:209], v149 offset:38912
	ds_read_b128 v[210:213], v149 offset:39936
	global_load_lds_dwordx4 v[222:223], off
	v_lshl_add_u64 v[222:223], s[24:25], 0, v[132:133]
	s_mov_b32 m0, s41
	s_nop 0
	global_load_lds_dwordx4 v[222:223], off
	s_waitcnt vmcnt(8)
	s_waitcnt lgkmcnt(0)
	s_barrier
	s_setprio 1
	s_waitcnt lgkmcnt(0)
	v_mfma_f32_16x16x32_bf16 v[126:129], v[150:153], v[182:185], v[126:129]
	v_mfma_f32_16x16x32_bf16 v[122:125], v[158:161], v[182:185], v[122:125]
	v_mfma_f32_16x16x32_bf16 v[114:117], v[150:153], v[190:193], v[114:117]
	v_mfma_f32_16x16x32_bf16 v[106:109], v[158:161], v[190:193], v[106:109]
	v_mfma_f32_16x16x32_bf16 v[98:101], v[150:153], v[198:201], v[98:101]
	v_mfma_f32_16x16x32_bf16 v[90:93], v[158:161], v[198:201], v[90:93]
	v_mfma_f32_16x16x32_bf16 v[82:85], v[150:153], v[206:209], v[82:85]
	v_mfma_f32_16x16x32_bf16 v[74:77], v[158:161], v[206:209], v[74:77]
	v_mfma_f32_16x16x32_bf16 v[126:129], v[154:157], v[186:189], v[126:129]
	v_mfma_f32_16x16x32_bf16 v[122:125], v[162:165], v[186:189], v[122:125]
	v_mfma_f32_16x16x32_bf16 v[114:117], v[154:157], v[194:197], v[114:117]
	v_mfma_f32_16x16x32_bf16 v[106:109], v[162:165], v[194:197], v[106:109]
	v_mfma_f32_16x16x32_bf16 v[98:101], v[154:157], v[202:205], v[98:101]
	v_mfma_f32_16x16x32_bf16 v[90:93], v[162:165], v[202:205], v[90:93]
	v_mfma_f32_16x16x32_bf16 v[82:85], v[154:157], v[210:213], v[82:85]
	v_mfma_f32_16x16x32_bf16 v[74:77], v[162:165], v[210:213], v[74:77]
	s_setprio 0
	s_setprio 1
	v_mfma_f32_16x16x32_bf16 v[118:121], v[166:169], v[182:185], v[118:121]
	v_mfma_f32_16x16x32_bf16 v[110:113], v[174:177], v[182:185], v[110:113]
	v_mfma_f32_16x16x32_bf16 v[102:105], v[166:169], v[190:193], v[102:105]
	v_mfma_f32_16x16x32_bf16 v[94:97], v[174:177], v[190:193], v[94:97]
	v_mfma_f32_16x16x32_bf16 v[86:89], v[166:169], v[198:201], v[86:89]
	v_mfma_f32_16x16x32_bf16 v[78:81], v[174:177], v[198:201], v[78:81]
	v_mfma_f32_16x16x32_bf16 v[70:73], v[166:169], v[206:209], v[70:73]
	v_mfma_f32_16x16x32_bf16 v[66:69], v[174:177], v[206:209], v[66:69]
	v_mfma_f32_16x16x32_bf16 v[118:121], v[170:173], v[186:189], v[118:121]
	v_mfma_f32_16x16x32_bf16 v[110:113], v[178:181], v[186:189], v[110:113]
	v_mfma_f32_16x16x32_bf16 v[102:105], v[170:173], v[194:197], v[102:105]
	v_mfma_f32_16x16x32_bf16 v[94:97], v[178:181], v[194:197], v[94:97]
	v_mfma_f32_16x16x32_bf16 v[86:89], v[170:173], v[202:205], v[86:89]
	s_setprio 2
	s_barrier
; #define PG8_STAGE(bufoff, gbase, voff) do { _Pragma("unroll") for (int _i = 0; _i < 2; ++_i) \
;         __builtin_amdgcn_global_load_lds((const unsigned*)((const char*)(gbase) + (voff)[_i]), (PG8_LAS unsigned*)(lds + (bufoff) + ldsw + _i * 8192), 16, 0, 0); } while (0)
; #define PG8_LDA(dst, b, h) do { _Pragma("unroll") for (int m = 0; m < 4; ++m) _Pragma("unroll") for (int k = 0; k < 2; ++k) dst[m][k] = *(const PG8_LAS bf16x8*)(lds + PG8_SA(b, h) + aoff + m * 2048 + k * 1024); } while (0)
; #define PG8_MMA(ai, bj, At, Bt) do { __builtin_amdgcn_s_setprio(1); _Pragma("unroll") for (int m = 0; m < 4; ++m) _Pragma("unroll") for (int n = 0; n < 2; ++n) _Pragma("unroll") for (int k = 0; k < 2; ++k) \
;         acc[ai][bj][m][n] = __builtin_amdgcn_mfma_f32_16x16x32_bf16(Bt[n][k], At[m][k], acc[ai][bj][m][n], 0, 0, 0); __builtin_amdgcn_s_setprio(0); } while (0)
; #define PG8_WAIT_V(n) asm volatile("s_waitcnt vmcnt(" #n ")" ::: "memory")
; #define PG8_WAIT_L(n) asm volatile("s_waitcnt lgkmcnt(" #n ")" ::: "memory")
; #define PG8_BAR __builtin_amdgcn_s_barrier()
; #define PG8_SCHED __builtin_amdgcn_sched_barrier(0)
; template <class Epi, class Sched, bool ALIGN_EPI = false, bool SP2 = false>
; __device__ __forceinline__ void gemm_phase(PG8_LAS unsigned char* lds, const Gemm g, const Sched& S, const Epi& E) {
;     ...
;             PG8_WAIT_V(8); PG8_WAIT_L(0); PG8_BAR; PG8_MMA(0, 0, At, B0); PG8_MMA(0, 1, At, B1); PG8_BAR; PG8_SCHED;
;             PG8_LDA(At, 1, 1); PG8_STAGE(PG8_SB(1, 0), b3, voffB); PG8_STAGE(PG8_SB(1, 1), b3 + hstep, voffB); PG8_STAGE(PG8_SA(1, 0), a3, voffA);
;             PG8_WAIT_V(8); PG8_WAIT_L(0); PG8_BAR; PG8_MMA(1, 0, At, B0); PG8_MMA(1, 1, At, B1); PG8_BAR; PG8_SCHED;
	v_mfma_f32_16x16x32_bf16 v[78:81], v[178:181], v[202:205], v[78:81]
	v_mfma_f32_16x16x32_bf16 v[70:73], v[170:173], v[210:213], v[70:73]
	v_mfma_f32_16x16x32_bf16 v[66:69], v[178:181], v[210:213], v[66:69]
	s_setprio 0
	s_add_i32 s24, s51, s38
	v_lshl_add_u64 v[214:215], v[214:215], 0, s[10:11]
	s_mov_b32 m0, s24
	ds_read_b128 v[182:185], v149 offset:49152
	ds_read_b128 v[186:189], v149 offset:50176
	ds_read_b128 v[190:193], v149 offset:51200
	ds_read_b128 v[194:197], v149 offset:52224
	ds_read_b128 v[198:201], v149 offset:53248
	ds_read_b128 v[202:205], v149 offset:54272
	ds_read_b128 v[206:209], v149 offset:55296
	ds_read_b128 v[210:213], v149 offset:56320
	global_load_lds_dwordx4 v[214:215], off
	s_add_i32 m0, s24, 0x2000
	s_add_u32 s22, s22, 0x40080
	v_lshl_add_u64 v[214:215], v[216:217], 0, s[10:11]
	s_addc_u32 s23, s23, 0
	s_add_i32 s24, s52, s38
	global_load_lds_dwordx4 v[214:215], off
	v_lshl_add_u64 v[214:215], s[22:23], 0, v[130:131]
	s_mov_b32 m0, s24
	s_nop 0
	global_load_lds_dwordx4 v[214:215], off
	v_lshl_add_u64 v[214:215], s[22:23], 0, v[132:133]
	s_add_i32 m0, s24, 0x2000
	s_nop 0
	global_load_lds_dwordx4 v[214:215], off
	v_lshl_add_u64 v[214:215], v[218:219], 0, s[10:11]
	s_mov_b32 m0, s42
	s_nop 0
	global_load_lds_dwordx4 v[214:215], off
	v_lshl_add_u64 v[214:215], v[220:221], 0, s[10:11]
	s_mov_b32 m0, s43
	s_nop 0
	global_load_lds_dwordx4 v[214:215], off
	s_waitcnt vmcnt(8)
	s_waitcnt lgkmcnt(0)
	s_barrier
	s_setprio 1
	s_waitcnt lgkmcnt(0)
	v_mfma_f32_16x16x32_bf16 v[62:65], v[150:153], v[182:185], v[62:65]
	v_mfma_f32_16x16x32_bf16 v[58:61], v[158:161], v[182:185], v[58:61]
	v_mfma_f32_16x16x32_bf16 v[50:53], v[150:153], v[190:193], v[50:53]
	v_mfma_f32_16x16x32_bf16 v[42:45], v[158:161], v[190:193], v[42:45]
	v_mfma_f32_16x16x32_bf16 v[34:37], v[150:153], v[198:201], v[34:37]
	v_mfma_f32_16x16x32_bf16 v[26:29], v[158:161], v[198:201], v[26:29]
	v_mfma_f32_16x16x32_bf16 v[18:21], v[150:153], v[206:209], v[18:21]
	v_mfma_f32_16x16x32_bf16 v[10:13], v[158:161], v[206:209], v[10:13]
	v_mfma_f32_16x16x32_bf16 v[62:65], v[154:157], v[186:189], v[62:65]
	v_mfma_f32_16x16x32_bf16 v[58:61], v[162:165], v[186:189], v[58:61]
	v_mfma_f32_16x16x32_bf16 v[50:53], v[154:157], v[194:197], v[50:53]
	v_mfma_f32_16x16x32_bf16 v[42:45], v[162:165], v[194:197], v[42:45]
	v_mfma_f32_16x16x32_bf16 v[34:37], v[154:157], v[202:205], v[34:37]
	v_mfma_f32_16x16x32_bf16 v[26:29], v[162:165], v[202:205], v[26:29]
	v_mfma_f32_16x16x32_bf16 v[18:21], v[154:157], v[210:213], v[18:21]
	v_mfma_f32_16x16x32_bf16 v[10:13], v[162:165], v[210:213], v[10:13]
	s_setprio 0
	s_setprio 1
	v_mfma_f32_16x16x32_bf16 v[54:57], v[166:169], v[182:185], v[54:57]
	v_mfma_f32_16x16x32_bf16 v[46:49], v[174:177], v[182:185], v[46:49]
	v_mfma_f32_16x16x32_bf16 v[38:41], v[166:169], v[190:193], v[38:41]
	v_mfma_f32_16x16x32_bf16 v[30:33], v[174:177], v[190:193], v[30:33]
	v_mfma_f32_16x16x32_bf16 v[22:25], v[166:169], v[198:201], v[22:25]
	v_mfma_f32_16x16x32_bf16 v[14:17], v[174:177], v[198:201], v[14:17]
	v_mfma_f32_16x16x32_bf16 v[6:9], v[166:169], v[206:209], v[6:9]
	v_mfma_f32_16x16x32_bf16 v[2:5], v[174:177], v[206:209], v[2:5]
	v_mfma_f32_16x16x32_bf16 v[54:57], v[170:173], v[186:189], v[54:57]
	v_mfma_f32_16x16x32_bf16 v[46:49], v[178:181], v[186:189], v[46:49]
	v_mfma_f32_16x16x32_bf16 v[38:41], v[170:173], v[194:197], v[38:41]
	v_mfma_f32_16x16x32_bf16 v[30:33], v[178:181], v[194:197], v[30:33]
	v_mfma_f32_16x16x32_bf16 v[22:25], v[170:173], v[202:205], v[22:25]
	s_setprio 2
	s_barrier
; #define PG8_STAGE(bufoff, gbase, voff) do { _Pragma("unroll") for (int _i = 0; _i < 2; ++_i) \
;         __builtin_amdgcn_global_load_lds((const unsigned*)((const char*)(gbase) + (voff)[_i]), (PG8_LAS unsigned*)(lds + (bufoff) + ldsw + _i * 8192), 16, 0, 0); } while (0)
; #define PG8_LDA(dst, b, h) do { _Pragma("unroll") for (int m = 0; m < 4; ++m) _Pragma("unroll") for (int k = 0; k < 2; ++k) dst[m][k] = *(const PG8_LAS bf16x8*)(lds + PG8_SA(b, h) + aoff + m * 2048 + k * 1024); } while (0)
; #define PG8_MMA(ai, bj, At, Bt) do { __builtin_amdgcn_s_setprio(1); _Pragma("unroll") for (int m = 0; m < 4; ++m) _Pragma("unroll") for (int n = 0; n < 2; ++n) _Pragma("unroll") for (int k = 0; k < 2; ++k) \
;         acc[ai][bj][m][n] = __builtin_amdgcn_mfma_f32_16x16x32_bf16(Bt[n][k], At[m][k], acc[ai][bj][m][n], 0, 0, 0); __builtin_amdgcn_s_setprio(0); } while (0)
; #define PG8_WAIT_V(n) asm volatile("s_waitcnt vmcnt(" #n ")" ::: "memory")
; #define PG8_WAIT_L(n) asm volatile("s_waitcnt lgkmcnt(" #n ")" ::: "memory")
; #define PG8_BAR __builtin_amdgcn_s_barrier()
; #define PG8_SCHED __builtin_amdgcn_sched_barrier(0)
; template <class Epi, class Sched, bool ALIGN_EPI = false, bool SP2 = false>
; __device__ __forceinline__ void gemm_phase(PG8_LAS unsigned char* lds, const Gemm g, const Sched& S, const Epi& E) {
;     ...
;             PG8_WAIT_V(8); PG8_WAIT_L(0); PG8_BAR; PG8_MMA(0, 0, At, B0); PG8_MMA(0, 1, At, B1); PG8_BAR; PG8_SCHED;
;             PG8_LDA(At, 1, 1); PG8_STAGE(PG8_SB(1, 0), b3, voffB); PG8_STAGE(PG8_SB(1, 1), b3 + hstep, voffB); PG8_STAGE(PG8_SA(1, 0), a3, voffA);
;             PG8_WAIT_V(8); PG8_WAIT_L(0); PG8_BAR; PG8_MMA(1, 0, At, B0); PG8_MMA(1, 1, At, B1); PG8_BAR; PG8_SCHED;
;     ...
;         if (!has_next) break;
; #pragma unroll
;         for (int a = 0; a < 2; ++a)
; #pragma unroll
;             for (int b = 0; b < 2; ++b)
; #pragma unroll
;                 for (int m = 0; m < 4; ++m)
; #pragma unroll
;                     for (int n = 0; n < 2; ++n) acc[a][b][m][n] = (f32x4){0.f, 0.f, 0.f, 0.f};
;         cur = nxt; cA = nA; cB = nB; ++ui;
	v_mfma_f32_16x16x32_bf16 v[14:17], v[178:181], v[202:205], v[14:17]
	v_mfma_f32_16x16x32_bf16 v[6:9], v[170:173], v[210:213], v[6:9]
	v_mfma_f32_16x16x32_bf16 v[2:5], v[178:181], v[210:213], v[2:5]
	s_setprio 0
	s_add_i32 s50, s50, 2
	s_add_u32 s20, s20, 0x100
	s_addc_u32 s21, s21, 0
	s_cmp_gt_u32 s50, 13
	s_cbranch_scc0 .LBB0_968
	s_add_u32 s20, s48, 0xffffff00
	s_addc_u32 s21, s49, -1
	s_andn2_b64 vcc, exec, s[2:3]
	s_cbranch_vccnz .LBB0_959
	v_mov_b32_e32 v2, 0
	s_mov_b32 s6, s12
	s_mov_b32 s4, s14
	s_mov_b64 s[8:9], s[18:19]
	s_mov_b32 s44, s47
	v_mov_b32_e32 v3, v2
	v_mov_b32_e32 v4, v2
	v_mov_b32_e32 v5, v2
	v_mov_b32_e32 v6, v2
	v_mov_b32_e32 v7, v2
	v_mov_b32_e32 v8, v2
	v_mov_b32_e32 v9, v2
	v_mov_b32_e32 v14, v2
	v_mov_b32_e32 v15, v2
	v_mov_b32_e32 v16, v2
	v_mov_b32_e32 v17, v2
	v_mov_b32_e32 v22, v2
	v_mov_b32_e32 v23, v2
	v_mov_b32_e32 v24, v2
	v_mov_b32_e32 v25, v2
	v_mov_b32_e32 v30, v2
	v_mov_b32_e32 v31, v2
	v_mov_b32_e32 v32, v2
	v_mov_b32_e32 v33, v2
	v_mov_b32_e32 v38, v2
	v_mov_b32_e32 v39, v2
	v_mov_b32_e32 v40, v2
	v_mov_b32_e32 v41, v2
	v_mov_b32_e32 v46, v2
	v_mov_b32_e32 v47, v2
	v_mov_b32_e32 v48, v2
	v_mov_b32_e32 v49, v2
	v_mov_b32_e32 v54, v2
	v_mov_b32_e32 v55, v2
	v_mov_b32_e32 v56, v2
	v_mov_b32_e32 v57, v2
	v_mov_b32_e32 v10, v2
	v_mov_b32_e32 v11, v2
	v_mov_b32_e32 v12, v2
	v_mov_b32_e32 v13, v2
	v_mov_b32_e32 v18, v2
	v_mov_b32_e32 v19, v2
	v_mov_b32_e32 v20, v2
	v_mov_b32_e32 v21, v2
	v_mov_b32_e32 v26, v2
	v_mov_b32_e32 v27, v2
	v_mov_b32_e32 v28, v2
	v_mov_b32_e32 v29, v2
	v_mov_b32_e32 v34, v2
	v_mov_b32_e32 v35, v2
	v_mov_b32_e32 v36, v2
	v_mov_b32_e32 v37, v2
	v_mov_b32_e32 v42, v2
	v_mov_b32_e32 v43, v2
	v_mov_b32_e32 v44, v2
	v_mov_b32_e32 v45, v2
	v_mov_b32_e32 v50, v2
	v_mov_b32_e32 v51, v2
	v_mov_b32_e32 v52, v2
	v_mov_b32_e32 v53, v2
	v_mov_b32_e32 v58, v2
	v_mov_b32_e32 v59, v2
	v_mov_b32_e32 v60, v2
	v_mov_b32_e32 v61, v2
	v_mov_b32_e32 v62, v2
	v_mov_b32_e32 v63, v2
	v_mov_b32_e32 v64, v2
	v_mov_b32_e32 v65, v2
	v_mov_b32_e32 v66, v2
	v_mov_b32_e32 v67, v2
	v_mov_b32_e32 v68, v2
	v_mov_b32_e32 v69, v2
	v_mov_b32_e32 v70, v2
	v_mov_b32_e32 v71, v2
	v_mov_b32_e32 v72, v2
	v_mov_b32_e32 v73, v2
	v_mov_b32_e32 v78, v2
	v_mov_b32_e32 v79, v2
	v_mov_b32_e32 v80, v2
	v_mov_b32_e32 v81, v2
	v_mov_b32_e32 v86, v2
	v_mov_b32_e32 v87, v2
	v_mov_b32_e32 v88, v2
	v_mov_b32_e32 v89, v2
	v_mov_b32_e32 v94, v2
	v_mov_b32_e32 v95, v2
	v_mov_b32_e32 v96, v2
	v_mov_b32_e32 v97, v2
	v_mov_b32_e32 v102, v2
	v_mov_b32_e32 v103, v2
	v_mov_b32_e32 v104, v2
	v_mov_b32_e32 v105, v2
	v_mov_b32_e32 v110, v2
	v_mov_b32_e32 v111, v2
	v_mov_b32_e32 v112, v2
	v_mov_b32_e32 v113, v2
	v_mov_b32_e32 v118, v2
	v_mov_b32_e32 v119, v2
	v_mov_b32_e32 v120, v2
	v_mov_b32_e32 v121, v2
	v_mov_b32_e32 v74, v2
	v_mov_b32_e32 v75, v2
	v_mov_b32_e32 v76, v2
	v_mov_b32_e32 v77, v2
	v_mov_b32_e32 v82, v2
	v_mov_b32_e32 v83, v2
	v_mov_b32_e32 v84, v2
	v_mov_b32_e32 v85, v2
	v_mov_b32_e32 v90, v2
	v_mov_b32_e32 v91, v2
	v_mov_b32_e32 v92, v2
	v_mov_b32_e32 v93, v2
	v_mov_b32_e32 v98, v2
	v_mov_b32_e32 v99, v2
	v_mov_b32_e32 v100, v2
	v_mov_b32_e32 v101, v2
	v_mov_b32_e32 v106, v2
	v_mov_b32_e32 v107, v2
	v_mov_b32_e32 v108, v2
	v_mov_b32_e32 v109, v2
	v_mov_b32_e32 v114, v2
	v_mov_b32_e32 v115, v2
	v_mov_b32_e32 v116, v2
	v_mov_b32_e32 v117, v2
	v_mov_b32_e32 v122, v2
	v_mov_b32_e32 v123, v2
	v_mov_b32_e32 v124, v2
	v_mov_b32_e32 v125, v2
	v_mov_b32_e32 v126, v2
	v_mov_b32_e32 v127, v2
	v_mov_b32_e32 v128, v2
	v_mov_b32_e32 v129, v2
	s_andn2_b64 vcc, exec, s[0:1]
	s_cbranch_vccnz .LBB0_960
